# GEMM 8-phase loops: per-segment s_setprio toggling removed (s_nop), on top of v31
# speedup vs baseline: 1.0089x; 1.0062x over previous
; #define PG8_STAGE(bufoff, gbase, voff) do { _Pragma("unroll") for (int _i = 0; _i < 2; ++_i) \
;         __builtin_amdgcn_global_load_lds((const unsigned*)((const char*)(gbase) + (voff)[_i]), (PG8_LAS unsigned*)(lds + (bufoff) + ldsw + _i * 8192), 16, 0, 0); } while (0)
; #define PG8_LDA(dst, b, h) do { _Pragma("unroll") for (int m = 0; m < 4; ++m) _Pragma("unroll") for (int k = 0; k < 2; ++k) dst[m][k] = *(const PG8_LAS bf16x8*)(lds + PG8_SA(b, h) + aoff + m * 2048 + k * 1024); } while (0)
; #define PG8_LDB(dst, b, h) do { _Pragma("unroll") for (int n = 0; n < 2; ++n) _Pragma("unroll") for (int k = 0; k < 2; ++k) dst[n][k] = *(const PG8_LAS bf16x8*)(lds + PG8_SB(b, h) + boff + n * 2048 + k * 1024); } while (0)
; #define PG8_MMA(ai, bj, At, Bt) do { __builtin_amdgcn_s_setprio(1); _Pragma("unroll") for (int m = 0; m < 4; ++m) _Pragma("unroll") for (int n = 0; n < 2; ++n) _Pragma("unroll") for (int k = 0; k < 2; ++k) \
;         acc[ai][bj][m][n] = __builtin_amdgcn_mfma_f32_16x16x32_bf16(Bt[n][k], At[m][k], acc[ai][bj][m][n], 0, 0, 0); __builtin_amdgcn_s_setprio(0); } while (0)
; #define PG8_WAIT_V(n) asm volatile("s_waitcnt vmcnt(" #n ")" ::: "memory")
; template <class Epi, class Sched, bool ALIGN_EPI = false, bool SP2 = false>
; __device__ __forceinline__ void gemm_phase(PG8_LAS unsigned char* lds, const Gemm g, const Sched& S, const Epi& E) {
;     ...
;             PG8_LDB(B0, 0, 0); PG8_LDB(B1, 0, 1); PG8_SCHED; PG8_LDA(At, 0, 0); PG8_STAGE(PG8_SA(1, 1), a1 + hstep, voffA);
;             PG8_WAIT_V(8); PG8_WAIT_L(0); PG8_BAR; PG8_MMA(0, 0, At, B0); PG8_MMA(0, 1, At, B1); PG8_BAR; PG8_SCHED;
;             PG8_LDA(At, 0, 1); PG8_STAGE(PG8_SB(0, 0), b2, voffB); PG8_STAGE(PG8_SB(0, 1), b2 + hstep, voffB); PG8_STAGE(PG8_SA(0, 0), a2, voffA);
;             PG8_WAIT_V(8); PG8_WAIT_L(0); PG8_BAR; PG8_MMA(1, 0, At, B0); PG8_MMA(1, 1, At, B1); PG8_BAR; PG8_SCHED;
;             PG8_LDB(B0, 1, 0); PG8_LDB(B1, 1, 1); PG8_SCHED; PG8_LDA(At, 1, 0); PG8_STAGE(PG8_SA(0, 1), a2 + hstep, voffA);
;             PG8_WAIT_V(8); PG8_WAIT_L(0); PG8_BAR; PG8_MMA(0, 0, At, B0); PG8_MMA(0, 1, At, B1); PG8_BAR; PG8_SCHED;
;             PG8_LDA(At, 1, 1); PG8_STAGE(PG8_SB(1, 0), b3, voffB); PG8_STAGE(PG8_SB(1, 1), b3 + hstep, voffB); PG8_STAGE(PG8_SA(1, 0), a3, voffA);
;             PG8_WAIT_V(8); PG8_WAIT_L(0); PG8_BAR; PG8_MMA(1, 0, At, B0); PG8_MMA(1, 1, At, B1); PG8_BAR; PG8_SCHED;
.LBB0_199:
	v_or_b32_e32 v156, 0x10000, v161
	v_add_u32_e32 v171, 0x10400, v161
	ds_read_b128 v[156:159], v156
	ds_read_b128 v[172:175], v171
	v_add_u32_e32 v171, 0x10800, v161
	v_add_u32_e32 v180, 0x10c00, v161
	ds_read_b128 v[176:179], v171
	ds_read_b128 v[180:183], v180
	v_or_b32_e32 v171, 0x14000, v161
	v_add_u32_e32 v188, 0x14400, v161
	ds_read_b128 v[184:187], v171
	ds_read_b128 v[188:191], v188
	v_add_u32_e32 v171, 0x14800, v161
	v_add_u32_e32 v196, 0x14c00, v161
	ds_read_b128 v[192:195], v171
	ds_read_b128 v[196:199], v196
	s_add_u32 s0, s2, 0xfff80080
	s_addc_u32 s1, s3, -1
	s_cmp_eq_u32 vcc_lo, 28
	s_cselect_b32 s19, s57, s1
	s_cselect_b32 s18, s60, s0
	s_cselect_b32 s17, s61, s97
	s_cselect_b32 s16, s79, s96
	s_mov_b32 m0, s39
	v_lshl_add_u64 v[204:205], s[2:3], 0, v[152:153]
	ds_read_b128 v[200:203], v160
	ds_read_b128 v[210:213], v160 offset:1024
	ds_read_b128 v[214:217], v160 offset:2048
	ds_read_b128 v[218:221], v160 offset:3072
	ds_read_b128 v[222:225], v160 offset:4096
	ds_read_b128 v[226:229], v160 offset:5120
	ds_read_b128 v[246:249], v160 offset:6144
	ds_read_b128 v[250:253], v160 offset:7168
	global_load_lds_dwordx4 v[204:205], off
	v_lshl_add_u64 v[204:205], s[2:3], 0, v[154:155]
	s_mov_b32 m0, s62
	s_nop 0
	global_load_lds_dwordx4 v[204:205], off
	s_waitcnt vmcnt(8)
	s_waitcnt lgkmcnt(0)
	s_barrier
	s_nop 0
	s_waitcnt lgkmcnt(0)
	v_mfma_f32_16x16x32_bf16 v[126:129], v[156:159], v[200:203], v[126:129]
	v_mfma_f32_16x16x32_bf16 v[122:125], v[176:179], v[200:203], v[122:125]
	v_mfma_f32_16x16x32_bf16 v[110:113], v[156:159], v[214:217], v[110:113]
	v_mfma_f32_16x16x32_bf16 v[106:109], v[176:179], v[214:217], v[106:109]
	v_mfma_f32_16x16x32_bf16 v[94:97], v[156:159], v[222:225], v[94:97]
	v_mfma_f32_16x16x32_bf16 v[90:93], v[176:179], v[222:225], v[90:93]
	v_mfma_f32_16x16x32_bf16 v[78:81], v[156:159], v[246:249], v[78:81]
	v_mfma_f32_16x16x32_bf16 v[74:77], v[176:179], v[246:249], v[74:77]
	v_mfma_f32_16x16x32_bf16 v[126:129], v[172:175], v[210:213], v[126:129]
	v_mfma_f32_16x16x32_bf16 v[122:125], v[180:183], v[210:213], v[122:125]
	v_mfma_f32_16x16x32_bf16 v[110:113], v[172:175], v[218:221], v[110:113]
	v_mfma_f32_16x16x32_bf16 v[106:109], v[180:183], v[218:221], v[106:109]
	v_mfma_f32_16x16x32_bf16 v[94:97], v[172:175], v[226:229], v[94:97]
	v_mfma_f32_16x16x32_bf16 v[90:93], v[180:183], v[226:229], v[90:93]
	v_mfma_f32_16x16x32_bf16 v[78:81], v[172:175], v[250:253], v[78:81]
	v_mfma_f32_16x16x32_bf16 v[74:77], v[180:183], v[250:253], v[74:77]
	s_nop 0
	s_nop 0
	v_mfma_f32_16x16x32_bf16 v[118:121], v[184:187], v[200:203], v[118:121]
	v_mfma_f32_16x16x32_bf16 v[114:117], v[192:195], v[200:203], v[114:117]
	v_mfma_f32_16x16x32_bf16 v[102:105], v[184:187], v[214:217], v[102:105]
	v_mfma_f32_16x16x32_bf16 v[98:101], v[192:195], v[214:217], v[98:101]
	v_mfma_f32_16x16x32_bf16 v[86:89], v[184:187], v[222:225], v[86:89]
	v_mfma_f32_16x16x32_bf16 v[82:85], v[192:195], v[222:225], v[82:85]
	v_mfma_f32_16x16x32_bf16 v[70:73], v[184:187], v[246:249], v[70:73]
	v_mfma_f32_16x16x32_bf16 v[66:69], v[192:195], v[246:249], v[66:69]
	v_mfma_f32_16x16x32_bf16 v[118:121], v[188:191], v[210:213], v[118:121]
	v_mfma_f32_16x16x32_bf16 v[114:117], v[196:199], v[210:213], v[114:117]
	v_mfma_f32_16x16x32_bf16 v[102:105], v[188:191], v[218:221], v[102:105]
	v_mfma_f32_16x16x32_bf16 v[98:101], v[196:199], v[218:221], v[98:101]
	v_mfma_f32_16x16x32_bf16 v[86:89], v[188:191], v[226:229], v[86:89]
	v_mfma_f32_16x16x32_bf16 v[82:85], v[196:199], v[226:229], v[82:85]
	v_mfma_f32_16x16x32_bf16 v[70:73], v[188:191], v[250:253], v[70:73]
	v_mfma_f32_16x16x32_bf16 v[66:69], v[196:199], v[250:253], v[66:69]
	s_nop 0
	s_barrier
	s_mov_b32 m0, s21
	v_lshl_add_u64 v[204:205], s[16:17], 0, v[0:1]
	s_add_u32 s0, s16, 0x80000
	ds_read_b128 v[200:203], v160 offset:16384
	ds_read_b128 v[210:213], v160 offset:17408
	ds_read_b128 v[214:217], v160 offset:18432
	ds_read_b128 v[218:221], v160 offset:19456
	ds_read_b128 v[222:225], v160 offset:20480
	ds_read_b128 v[226:229], v160 offset:21504
	ds_read_b128 v[246:249], v160 offset:22528
	ds_read_b128 v[250:253], v160 offset:23552
	global_load_lds_dwordx4 v[204:205], off
	v_lshl_add_u64 v[230:231], s[16:17], 0, v[130:131]
	s_mov_b32 m0, s22
	s_addc_u32 s1, s17, 0
	global_load_lds_dwordx4 v[230:231], off
	v_lshl_add_u64 v[232:233], s[0:1], 0, v[0:1]
	s_mov_b32 m0, s23
	v_lshl_add_u64 v[234:235], s[18:19], 0, v[132:133]
	global_load_lds_dwordx4 v[232:233], off
	v_lshl_add_u64 v[232:233], s[0:1], 0, v[130:131]
	s_mov_b32 m0, s24
	s_nop 0
	global_load_lds_dwordx4 v[232:233], off
	v_lshl_add_u64 v[232:233], s[18:19], 0, v[134:135]
	s_mov_b32 m0, s20
	s_nop 0
	global_load_lds_dwordx4 v[232:233], off
	s_mov_b32 m0, s25
	s_nop 0
	global_load_lds_dwordx4 v[234:235], off
	s_waitcnt vmcnt(8)
	s_waitcnt lgkmcnt(0)
	s_barrier
; #define PG8_STAGE(bufoff, gbase, voff) do { _Pragma("unroll") for (int _i = 0; _i < 2; ++_i) \
;         __builtin_amdgcn_global_load_lds((const unsigned*)((const char*)(gbase) + (voff)[_i]), (PG8_LAS unsigned*)(lds + (bufoff) + ldsw + _i * 8192), 16, 0, 0); } while (0)
; #define PG8_LDA(dst, b, h) do { _Pragma("unroll") for (int m = 0; m < 4; ++m) _Pragma("unroll") for (int k = 0; k < 2; ++k) dst[m][k] = *(const PG8_LAS bf16x8*)(lds + PG8_SA(b, h) + aoff + m * 2048 + k * 1024); } while (0)
; #define PG8_LDB(dst, b, h) do { _Pragma("unroll") for (int n = 0; n < 2; ++n) _Pragma("unroll") for (int k = 0; k < 2; ++k) dst[n][k] = *(const PG8_LAS bf16x8*)(lds + PG8_SB(b, h) + boff + n * 2048 + k * 1024); } while (0)
; #define PG8_MMA(ai, bj, At, Bt) do { __builtin_amdgcn_s_setprio(1); _Pragma("unroll") for (int m = 0; m < 4; ++m) _Pragma("unroll") for (int n = 0; n < 2; ++n) _Pragma("unroll") for (int k = 0; k < 2; ++k) \
;         acc[ai][bj][m][n] = __builtin_amdgcn_mfma_f32_16x16x32_bf16(Bt[n][k], At[m][k], acc[ai][bj][m][n], 0, 0, 0); __builtin_amdgcn_s_setprio(0); } while (0)
; #define PG8_WAIT_V(n) asm volatile("s_waitcnt vmcnt(" #n ")" ::: "memory")
; template <class Epi, class Sched, bool ALIGN_EPI = false, bool SP2 = false>
; __device__ __forceinline__ void gemm_phase(PG8_LAS unsigned char* lds, const Gemm g, const Sched& S, const Epi& E) {
;     ...
;             PG8_LDB(B0, 0, 0); PG8_LDB(B1, 0, 1); PG8_SCHED; PG8_LDA(At, 0, 0); PG8_STAGE(PG8_SA(1, 1), a1 + hstep, voffA);
;             PG8_WAIT_V(8); PG8_WAIT_L(0); PG8_BAR; PG8_MMA(0, 0, At, B0); PG8_MMA(0, 1, At, B1); PG8_BAR; PG8_SCHED;
;             PG8_LDA(At, 0, 1); PG8_STAGE(PG8_SB(0, 0), b2, voffB); PG8_STAGE(PG8_SB(0, 1), b2 + hstep, voffB); PG8_STAGE(PG8_SA(0, 0), a2, voffA);
;             PG8_WAIT_V(8); PG8_WAIT_L(0); PG8_BAR; PG8_MMA(1, 0, At, B0); PG8_MMA(1, 1, At, B1); PG8_BAR; PG8_SCHED;
;             PG8_LDB(B0, 1, 0); PG8_LDB(B1, 1, 1); PG8_SCHED; PG8_LDA(At, 1, 0); PG8_STAGE(PG8_SA(0, 1), a2 + hstep, voffA);
;             PG8_WAIT_V(8); PG8_WAIT_L(0); PG8_BAR; PG8_MMA(0, 0, At, B0); PG8_MMA(0, 1, At, B1); PG8_BAR; PG8_SCHED;
;             PG8_LDA(At, 1, 1); PG8_STAGE(PG8_SB(1, 0), b3, voffB); PG8_STAGE(PG8_SB(1, 1), b3 + hstep, voffB); PG8_STAGE(PG8_SA(1, 0), a3, voffA);
;             PG8_WAIT_V(8); PG8_WAIT_L(0); PG8_BAR; PG8_MMA(1, 0, At, B0); PG8_MMA(1, 1, At, B1); PG8_BAR; PG8_SCHED;
	s_nop 0
	s_waitcnt lgkmcnt(0)
	v_mfma_f32_16x16x32_bf16 v[62:65], v[156:159], v[200:203], v[62:65]
	v_mfma_f32_16x16x32_bf16 v[58:61], v[176:179], v[200:203], v[58:61]
	v_mfma_f32_16x16x32_bf16 v[46:49], v[156:159], v[214:217], v[46:49]
	v_mfma_f32_16x16x32_bf16 v[42:45], v[176:179], v[214:217], v[42:45]
	v_mfma_f32_16x16x32_bf16 v[30:33], v[156:159], v[222:225], v[30:33]
	v_mfma_f32_16x16x32_bf16 v[26:29], v[176:179], v[222:225], v[26:29]
	v_mfma_f32_16x16x32_bf16 v[14:17], v[156:159], v[246:249], v[14:17]
	v_mfma_f32_16x16x32_bf16 v[10:13], v[176:179], v[246:249], v[10:13]
	v_mfma_f32_16x16x32_bf16 v[62:65], v[172:175], v[210:213], v[62:65]
	v_mfma_f32_16x16x32_bf16 v[58:61], v[180:183], v[210:213], v[58:61]
	v_mfma_f32_16x16x32_bf16 v[46:49], v[172:175], v[218:221], v[46:49]
	v_mfma_f32_16x16x32_bf16 v[42:45], v[180:183], v[218:221], v[42:45]
	v_mfma_f32_16x16x32_bf16 v[30:33], v[172:175], v[226:229], v[30:33]
	v_mfma_f32_16x16x32_bf16 v[26:29], v[180:183], v[226:229], v[26:29]
	v_mfma_f32_16x16x32_bf16 v[14:17], v[172:175], v[250:253], v[14:17]
	v_mfma_f32_16x16x32_bf16 v[10:13], v[180:183], v[250:253], v[10:13]
	s_nop 0
	s_nop 0
	v_mfma_f32_16x16x32_bf16 v[54:57], v[184:187], v[200:203], v[54:57]
	v_mfma_f32_16x16x32_bf16 v[50:53], v[192:195], v[200:203], v[50:53]
	v_mfma_f32_16x16x32_bf16 v[38:41], v[184:187], v[214:217], v[38:41]
	v_mfma_f32_16x16x32_bf16 v[34:37], v[192:195], v[214:217], v[34:37]
	v_mfma_f32_16x16x32_bf16 v[22:25], v[184:187], v[222:225], v[22:25]
	v_mfma_f32_16x16x32_bf16 v[18:21], v[192:195], v[222:225], v[18:21]
	v_mfma_f32_16x16x32_bf16 v[6:9], v[184:187], v[246:249], v[6:9]
	v_mfma_f32_16x16x32_bf16 v[2:5], v[192:195], v[246:249], v[2:5]
	v_mfma_f32_16x16x32_bf16 v[54:57], v[188:191], v[210:213], v[54:57]
	v_mfma_f32_16x16x32_bf16 v[50:53], v[196:199], v[210:213], v[50:53]
	v_mfma_f32_16x16x32_bf16 v[38:41], v[188:191], v[218:221], v[38:41]
	v_mfma_f32_16x16x32_bf16 v[34:37], v[196:199], v[218:221], v[34:37]
	v_mfma_f32_16x16x32_bf16 v[22:25], v[188:191], v[226:229], v[22:25]
	v_mfma_f32_16x16x32_bf16 v[18:21], v[196:199], v[226:229], v[18:21]
	v_mfma_f32_16x16x32_bf16 v[6:9], v[188:191], v[250:253], v[6:9]
	v_mfma_f32_16x16x32_bf16 v[2:5], v[196:199], v[250:253], v[2:5]
	s_nop 0
	s_barrier
	v_or_b32_e32 v156, 0x18000, v161
	v_add_u32_e32 v171, 0x18400, v161
	ds_read_b128 v[156:159], v156
	ds_read_b128 v[172:175], v171
	v_add_u32_e32 v171, 0x18800, v161
	v_add_u32_e32 v180, 0x18c00, v161
	ds_read_b128 v[176:179], v171
	ds_read_b128 v[180:183], v180
	v_or_b32_e32 v171, 0x1c000, v161
	v_add_u32_e32 v188, 0x1c400, v161
	ds_read_b128 v[184:187], v171
	ds_read_b128 v[188:191], v188
	v_add_u32_e32 v171, 0x1c800, v161
	v_add_u32_e32 v196, 0x1cc00, v161
	ds_read_b128 v[192:195], v171
	ds_read_b128 v[196:199], v196
	s_add_u32 s0, s18, 0x80000
	s_addc_u32 s1, s19, 0
	s_mov_b32 m0, s26
	v_lshl_add_u64 v[236:237], s[0:1], 0, v[134:135]
	ds_read_b128 v[200:203], v160 offset:32768
	ds_read_b128 v[210:213], v160 offset:33792
	ds_read_b128 v[214:217], v160 offset:34816
	ds_read_b128 v[218:221], v160 offset:35840
	ds_read_b128 v[222:225], v160 offset:36864
	ds_read_b128 v[226:229], v160 offset:37888
	ds_read_b128 v[246:249], v160 offset:38912
	ds_read_b128 v[250:253], v160 offset:39936
	global_load_lds_dwordx4 v[236:237], off
	v_lshl_add_u64 v[236:237], s[0:1], 0, v[132:133]
	s_mov_b32 m0, s27
	s_nop 0
	global_load_lds_dwordx4 v[236:237], off
	s_waitcnt vmcnt(8)
	s_waitcnt lgkmcnt(0)
	s_barrier
	s_nop 0
	s_waitcnt lgkmcnt(0)
	v_mfma_f32_16x16x32_bf16 v[126:129], v[156:159], v[200:203], v[126:129]
	v_mfma_f32_16x16x32_bf16 v[122:125], v[176:179], v[200:203], v[122:125]
	v_mfma_f32_16x16x32_bf16 v[110:113], v[156:159], v[214:217], v[110:113]
	v_mfma_f32_16x16x32_bf16 v[106:109], v[176:179], v[214:217], v[106:109]
	v_mfma_f32_16x16x32_bf16 v[94:97], v[156:159], v[222:225], v[94:97]
	v_mfma_f32_16x16x32_bf16 v[90:93], v[176:179], v[222:225], v[90:93]
	v_mfma_f32_16x16x32_bf16 v[78:81], v[156:159], v[246:249], v[78:81]
	v_mfma_f32_16x16x32_bf16 v[74:77], v[176:179], v[246:249], v[74:77]
	v_mfma_f32_16x16x32_bf16 v[126:129], v[172:175], v[210:213], v[126:129]
	v_mfma_f32_16x16x32_bf16 v[122:125], v[180:183], v[210:213], v[122:125]
	v_mfma_f32_16x16x32_bf16 v[110:113], v[172:175], v[218:221], v[110:113]
	v_mfma_f32_16x16x32_bf16 v[106:109], v[180:183], v[218:221], v[106:109]
	v_mfma_f32_16x16x32_bf16 v[94:97], v[172:175], v[226:229], v[94:97]
	v_mfma_f32_16x16x32_bf16 v[90:93], v[180:183], v[226:229], v[90:93]
	v_mfma_f32_16x16x32_bf16 v[78:81], v[172:175], v[250:253], v[78:81]
	v_mfma_f32_16x16x32_bf16 v[74:77], v[180:183], v[250:253], v[74:77]
	s_nop 0
	s_nop 0
	v_mfma_f32_16x16x32_bf16 v[118:121], v[184:187], v[200:203], v[118:121]
	v_mfma_f32_16x16x32_bf16 v[114:117], v[192:195], v[200:203], v[114:117]
	v_mfma_f32_16x16x32_bf16 v[102:105], v[184:187], v[214:217], v[102:105]
	v_mfma_f32_16x16x32_bf16 v[98:101], v[192:195], v[214:217], v[98:101]
	v_mfma_f32_16x16x32_bf16 v[86:89], v[184:187], v[222:225], v[86:89]
	v_mfma_f32_16x16x32_bf16 v[82:85], v[192:195], v[222:225], v[82:85]
	v_mfma_f32_16x16x32_bf16 v[70:73], v[184:187], v[246:249], v[70:73]
	v_mfma_f32_16x16x32_bf16 v[66:69], v[192:195], v[246:249], v[66:69]
	v_mfma_f32_16x16x32_bf16 v[118:121], v[188:191], v[210:213], v[118:121]
	v_mfma_f32_16x16x32_bf16 v[114:117], v[196:199], v[210:213], v[114:117]
	v_mfma_f32_16x16x32_bf16 v[102:105], v[188:191], v[218:221], v[102:105]
	v_mfma_f32_16x16x32_bf16 v[98:101], v[196:199], v[218:221], v[98:101]
	v_mfma_f32_16x16x32_bf16 v[86:89], v[188:191], v[226:229], v[86:89]
	v_mfma_f32_16x16x32_bf16 v[82:85], v[196:199], v[226:229], v[82:85]
	v_mfma_f32_16x16x32_bf16 v[70:73], v[188:191], v[250:253], v[70:73]
	v_mfma_f32_16x16x32_bf16 v[66:69], v[196:199], v[250:253], v[66:69]
	s_nop 0
	s_barrier
; #define PG8_STAGE(bufoff, gbase, voff) do { _Pragma("unroll") for (int _i = 0; _i < 2; ++_i) \
;         __builtin_amdgcn_global_load_lds((const unsigned*)((const char*)(gbase) + (voff)[_i]), (PG8_LAS unsigned*)(lds + (bufoff) + ldsw + _i * 8192), 16, 0, 0); } while (0)
; #define PG8_LDA(dst, b, h) do { _Pragma("unroll") for (int m = 0; m < 4; ++m) _Pragma("unroll") for (int k = 0; k < 2; ++k) dst[m][k] = *(const PG8_LAS bf16x8*)(lds + PG8_SA(b, h) + aoff + m * 2048 + k * 1024); } while (0)
; #define PG8_LDB(dst, b, h) do { _Pragma("unroll") for (int n = 0; n < 2; ++n) _Pragma("unroll") for (int k = 0; k < 2; ++k) dst[n][k] = *(const PG8_LAS bf16x8*)(lds + PG8_SB(b, h) + boff + n * 2048 + k * 1024); } while (0)
; #define PG8_MMA(ai, bj, At, Bt) do { __builtin_amdgcn_s_setprio(1); _Pragma("unroll") for (int m = 0; m < 4; ++m) _Pragma("unroll") for (int n = 0; n < 2; ++n) _Pragma("unroll") for (int k = 0; k < 2; ++k) \
;         acc[ai][bj][m][n] = __builtin_amdgcn_mfma_f32_16x16x32_bf16(Bt[n][k], At[m][k], acc[ai][bj][m][n], 0, 0, 0); __builtin_amdgcn_s_setprio(0); } while (0)
; #define PG8_WAIT_V(n) asm volatile("s_waitcnt vmcnt(" #n ")" ::: "memory")
; template <class Epi, class Sched, bool ALIGN_EPI = false, bool SP2 = false>
; __device__ __forceinline__ void gemm_phase(PG8_LAS unsigned char* lds, const Gemm g, const Sched& S, const Epi& E) {
;     ...
;             PG8_LDB(B0, 0, 0); PG8_LDB(B1, 0, 1); PG8_SCHED; PG8_LDA(At, 0, 0); PG8_STAGE(PG8_SA(1, 1), a1 + hstep, voffA);
;             PG8_WAIT_V(8); PG8_WAIT_L(0); PG8_BAR; PG8_MMA(0, 0, At, B0); PG8_MMA(0, 1, At, B1); PG8_BAR; PG8_SCHED;
;             PG8_LDA(At, 0, 1); PG8_STAGE(PG8_SB(0, 0), b2, voffB); PG8_STAGE(PG8_SB(0, 1), b2 + hstep, voffB); PG8_STAGE(PG8_SA(0, 0), a2, voffA);
;             PG8_WAIT_V(8); PG8_WAIT_L(0); PG8_BAR; PG8_MMA(1, 0, At, B0); PG8_MMA(1, 1, At, B1); PG8_BAR; PG8_SCHED;
;             PG8_LDB(B0, 1, 0); PG8_LDB(B1, 1, 1); PG8_SCHED; PG8_LDA(At, 1, 0); PG8_STAGE(PG8_SA(0, 1), a2 + hstep, voffA);
;             PG8_WAIT_V(8); PG8_WAIT_L(0); PG8_BAR; PG8_MMA(0, 0, At, B0); PG8_MMA(0, 1, At, B1); PG8_BAR; PG8_SCHED;
;             PG8_LDA(At, 1, 1); PG8_STAGE(PG8_SB(1, 0), b3, voffB); PG8_STAGE(PG8_SB(1, 1), b3 + hstep, voffB); PG8_STAGE(PG8_SA(1, 0), a3, voffA);
;             PG8_WAIT_V(8); PG8_WAIT_L(0); PG8_BAR; PG8_MMA(1, 0, At, B0); PG8_MMA(1, 1, At, B1); PG8_BAR; PG8_SCHED;
	s_mov_b32 m0, s28
	v_lshl_add_u64 v[204:205], v[204:205], 0, s[6:7]
	s_add_u32 s0, s16, 0x80080
	ds_read_b128 v[200:203], v160 offset:49152
	ds_read_b128 v[210:213], v160 offset:50176
	ds_read_b128 v[214:217], v160 offset:51200
	ds_read_b128 v[218:221], v160 offset:52224
	ds_read_b128 v[222:225], v160 offset:53248
	ds_read_b128 v[226:229], v160 offset:54272
	ds_read_b128 v[246:249], v160 offset:55296
	ds_read_b128 v[250:253], v160 offset:56320
	global_load_lds_dwordx4 v[204:205], off
	v_lshl_add_u64 v[204:205], v[230:231], 0, s[6:7]
	s_mov_b32 m0, s29
	s_addc_u32 s1, s17, 0
	global_load_lds_dwordx4 v[204:205], off
	v_lshl_add_u64 v[204:205], s[0:1], 0, v[0:1]
	s_mov_b32 m0, s34
	s_nop 0
	global_load_lds_dwordx4 v[204:205], off
	v_lshl_add_u64 v[204:205], s[0:1], 0, v[130:131]
	s_mov_b32 m0, s35
	s_nop 0
	global_load_lds_dwordx4 v[204:205], off
	v_lshl_add_u64 v[204:205], v[232:233], 0, s[6:7]
	s_mov_b32 m0, s30
	s_nop 0
	global_load_lds_dwordx4 v[204:205], off
	v_lshl_add_u64 v[204:205], v[234:235], 0, s[6:7]
	s_mov_b32 m0, s31
	s_nop 0
	global_load_lds_dwordx4 v[204:205], off
	s_waitcnt vmcnt(8)
	s_waitcnt lgkmcnt(0)
	s_barrier
	s_nop 0
	s_waitcnt lgkmcnt(0)
	v_mfma_f32_16x16x32_bf16 v[62:65], v[156:159], v[200:203], v[62:65]
	v_mfma_f32_16x16x32_bf16 v[58:61], v[176:179], v[200:203], v[58:61]
	v_mfma_f32_16x16x32_bf16 v[46:49], v[156:159], v[214:217], v[46:49]
	v_mfma_f32_16x16x32_bf16 v[42:45], v[176:179], v[214:217], v[42:45]
	v_mfma_f32_16x16x32_bf16 v[30:33], v[156:159], v[222:225], v[30:33]
	v_mfma_f32_16x16x32_bf16 v[26:29], v[176:179], v[222:225], v[26:29]
	v_mfma_f32_16x16x32_bf16 v[14:17], v[156:159], v[246:249], v[14:17]
	v_mfma_f32_16x16x32_bf16 v[10:13], v[176:179], v[246:249], v[10:13]
	v_mfma_f32_16x16x32_bf16 v[62:65], v[172:175], v[210:213], v[62:65]
	v_mfma_f32_16x16x32_bf16 v[58:61], v[180:183], v[210:213], v[58:61]
	v_mfma_f32_16x16x32_bf16 v[46:49], v[172:175], v[218:221], v[46:49]
	v_mfma_f32_16x16x32_bf16 v[42:45], v[180:183], v[218:221], v[42:45]
	v_mfma_f32_16x16x32_bf16 v[30:33], v[172:175], v[226:229], v[30:33]
	v_mfma_f32_16x16x32_bf16 v[26:29], v[180:183], v[226:229], v[26:29]
	v_mfma_f32_16x16x32_bf16 v[14:17], v[172:175], v[250:253], v[14:17]
	v_mfma_f32_16x16x32_bf16 v[10:13], v[180:183], v[250:253], v[10:13]
	s_nop 0
	s_nop 0
	v_mfma_f32_16x16x32_bf16 v[54:57], v[184:187], v[200:203], v[54:57]
	v_mfma_f32_16x16x32_bf16 v[50:53], v[192:195], v[200:203], v[50:53]
	v_mfma_f32_16x16x32_bf16 v[38:41], v[184:187], v[214:217], v[38:41]
	v_mfma_f32_16x16x32_bf16 v[34:37], v[192:195], v[214:217], v[34:37]
	v_mfma_f32_16x16x32_bf16 v[22:25], v[184:187], v[222:225], v[22:25]
	v_mfma_f32_16x16x32_bf16 v[18:21], v[192:195], v[222:225], v[18:21]
	v_mfma_f32_16x16x32_bf16 v[6:9], v[184:187], v[246:249], v[6:9]
	v_mfma_f32_16x16x32_bf16 v[2:5], v[192:195], v[246:249], v[2:5]
	v_mfma_f32_16x16x32_bf16 v[54:57], v[188:191], v[210:213], v[54:57]
	v_mfma_f32_16x16x32_bf16 v[50:53], v[196:199], v[210:213], v[50:53]
	v_mfma_f32_16x16x32_bf16 v[38:41], v[188:191], v[218:221], v[38:41]
	v_mfma_f32_16x16x32_bf16 v[34:37], v[196:199], v[218:221], v[34:37]
	v_mfma_f32_16x16x32_bf16 v[22:25], v[188:191], v[226:229], v[22:25]
	v_mfma_f32_16x16x32_bf16 v[18:21], v[196:199], v[226:229], v[18:21]
	v_mfma_f32_16x16x32_bf16 v[6:9], v[188:191], v[250:253], v[6:9]
	v_mfma_f32_16x16x32_bf16 v[2:5], v[196:199], v[250:253], v[2:5]
	s_nop 0
	s_barrier
	s_add_i32 vcc_lo, vcc_lo, 2
	s_add_u32 s2, s2, 0x100
	s_addc_u32 s3, s3, 0
	s_add_u32 s96, s96, 0x100
	s_addc_u32 s97, s97, 0
	s_cmp_gt_u32 vcc_lo, 29
	s_cbranch_scc0 .LBB0_199
	s_and_b64 vcc, exec, s[8:9]
	s_cbranch_vccz .LBB0_202
	s_barrier

.LBB0_642:
	v_sub_f32_e32 v3, v80, v2
	v_exp_f32_e32 v3, v3
	v_sub_f32_e32 v4, v81, v2
	v_exp_f32_e32 v4, v4
	v_sub_f32_e32 v5, v82, v2
	v_exp_f32_e32 v5, v5
	v_sub_f32_e32 v6, v83, v2
	v_exp_f32_e32 v6, v6
	v_sub_f32_e32 v8, v84, v2
	v_add_f32_e32 v7, 0, v3
	v_exp_f32_e32 v8, v8
	v_sub_f32_e32 v9, v85, v2
	v_add_f32_e32 v7, v4, v7
	v_exp_f32_e32 v9, v9
	v_sub_f32_e32 v10, v86, v2
	v_add_f32_e32 v7, v5, v7
	v_exp_f32_e32 v10, v10
	v_sub_f32_e32 v11, v87, v2
	v_add_f32_e32 v7, v6, v7
	v_exp_f32_e32 v11, v11
	v_sub_f32_e32 v12, v88, v2
	v_add_f32_e32 v7, v8, v7
	v_exp_f32_e32 v12, v12
	v_sub_f32_e32 v13, v89, v2
	v_add_f32_e32 v7, v9, v7
	v_exp_f32_e32 v13, v13
	v_sub_f32_e32 v14, v90, v2
	v_add_f32_e32 v7, v10, v7
	v_exp_f32_e32 v14, v14
	v_sub_f32_e32 v15, v91, v2
	v_add_f32_e32 v7, v11, v7
	v_exp_f32_e32 v15, v15
	v_sub_f32_e32 v80, v92, v2
	v_add_f32_e32 v7, v12, v7
	v_exp_f32_e32 v80, v80
	v_sub_f32_e32 v81, v93, v2
	v_add_f32_e32 v7, v13, v7
	v_exp_f32_e32 v81, v81
	v_sub_f32_e32 v82, v94, v2
	v_add_f32_e32 v7, v14, v7
	v_exp_f32_e32 v82, v82
	v_sub_f32_e32 v83, v95, v2
	v_add_f32_e32 v7, v15, v7
	v_exp_f32_e32 v83, v83
	v_add_f32_e32 v7, v80, v7
	v_add_f32_e32 v7, v81, v7
	v_add_f32_e32 v7, v82, v7
	v_add_f32_e32 v84, v83, v7
	v_fmac_f32_e32 v84, v212, v0
	v_cvt_pk_bf16_f32 v4, v3, v4
	v_cvt_pk_bf16_f32 v5, v5, v6
	v_cvt_pk_bf16_f32 v6, v8, v9
	v_cvt_pk_bf16_f32 v7, v10, v11
	v_cvt_pk_bf16_f32 v8, v12, v13
	v_cvt_pk_bf16_f32 v9, v14, v15
	v_cvt_pk_bf16_f32 v10, v80, v81
	v_cvt_pk_bf16_f32 v11, v82, v83
	s_nop 0
	ds_read_b64 v[12:13], v227 offset:0
	ds_read_b64 v[14:15], v227 offset:16
	ds_read_b64 v[230:231], v227 offset:32
	ds_read_b64 v[232:233], v227 offset:48
	ds_read_b64 v[234:235], v227 offset:4608
	ds_read_b64 v[236:237], v227 offset:4624
	ds_read_b64 v[246:247], v227 offset:4640
	ds_read_b64 v[248:249], v227 offset:4656
	ds_read_b64 v[250:251], v227 offset:9216
	ds_read_b64 v[252:253], v227 offset:9232
	s_waitcnt lgkmcnt(8)
	v_mfma_f32_32x32x16_bf16 v[64:79], v[12:15], v[4:7], v[64:79]
	ds_read_b64 v[12:13], v227 offset:9248
	ds_read_b64 v[14:15], v227 offset:9264
	s_waitcnt lgkmcnt(8)
	v_mfma_f32_32x32x16_bf16 v[64:79], v[230:233], v[8:11], v[64:79]
	ds_read_b64 v[230:231], v227 offset:13824
	ds_read_b64 v[232:233], v227 offset:13840
	s_waitcnt lgkmcnt(8)
	v_mfma_f32_32x32x16_bf16 v[48:63], v[234:237], v[4:7], v[48:63]
	ds_read_b64 v[234:235], v227 offset:13856
	ds_read_b64 v[236:237], v227 offset:13872
	s_waitcnt lgkmcnt(8)
	v_mfma_f32_32x32x16_bf16 v[48:63], v[246:249], v[8:11], v[48:63]
	s_waitcnt lgkmcnt(6)
	v_mfma_f32_32x32x16_bf16 v[32:47], v[250:253], v[4:7], v[32:47]
	s_waitcnt lgkmcnt(4)
	v_mfma_f32_32x32x16_bf16 v[32:47], v[12:15], v[8:11], v[32:47]
	s_waitcnt lgkmcnt(2)
	v_mfma_f32_32x32x16_bf16 v[16:31], v[230:233], v[4:7], v[16:31]
	s_waitcnt lgkmcnt(0)
	v_mfma_f32_32x32x16_bf16 v[16:31], v[234:237], v[8:11], v[16:31]
	s_nop 0
	v_mov_b32_e32 v229, v2
	v_mov_b32_e32 v212, v84

; #define AT_LOAD(RK, RV, T) { const size_t ko_ = (size_t)(T) * 64 * 192; const int vo_ = (T) * 64; \
;     _Pragma("unroll") for (int i = 0; i < 3; ++i) { const int id = tid + NT * i, row = id / 24, cc = id % 24; RK[i] = *(const u32x4*)(Kg + ko_ + row * 192 + cc * 8); } \
;     _Pragma("unroll") for (int i = 0; i < 2; ++i) RV[i] = *(const u32x4*)(Vg + (size_t)(vrow + 64 * i) * S_ + vo_ + vcc * 8); }
; #define AT_WRITE(RK, RV, ST) { char* dK = smem + (ST) * STG; \
;     _Pragma("unroll") for (int i = 0; i < 3; ++i) { const int id = tid + NT * i, row = id / 24, cc = id % 24; *(u32x4*)(dK + row * 400 + cc * 16) = RK[i]; } \
;     _Pragma("unroll") for (int i = 0; i < 2; ++i) *(u32x4*)(dK + KST + (vrow + 64 * i) * 144 + vcc * 16) = RV[i]; }
; DI void mla_attn_item(const Params& P, int hd, int b, char* smem) {
;     ...
;     AT_WRITE(rk1, rv1, 1);
;     AT_LOAD(rk1, rv1, (kt + 3 < ntl ? kt + 3 : ntl));
;     AT_COMPUTE(0, kt);
;     __syncthreads();
;     AT_WRITE(rk0, rv0, 0);
;     AT_LOAD(rk0, rv0, (kt + 4 < ntl ? kt + 4 : ntl));
;     AT_COMPUTE(1, kt + 1);
.LBB0_644:
	s_add_i32 s2, s60, 5
	s_min_u32 s2, s2, s57
	s_mul_i32 s62, s2, 0x6000
	v_lshl_add_u64 v[2:3], v[188:189], 0, s[62:63]
	v_lshl_add_u64 v[4:5], v[190:191], 1, v[2:3]
	s_waitcnt vmcnt(5)
	ds_write_b128 v217, v[136:139] offset:44032
	ds_write_b128 v218, v[140:143] offset:44032
	ds_write_b128 v219, v[144:147] offset:44032
	ds_write_b128 v226, v[148:151]
	ds_write_b128 v226, v[152:155] offset:9216
	v_lshl_add_u64 v[4:5], v[192:193], 1, v[4:5]
	v_lshl_add_u64 v[6:7], v[194:195], 1, v[2:3]
	v_lshl_add_u64 v[2:3], v[198:199], 1, v[2:3]
	s_lshl_b32 s62, s2, 7
	v_lshl_add_u64 v[6:7], v[196:197], 1, v[6:7]
	global_load_dwordx4 v[136:139], v[4:5], off
	global_load_dwordx4 v[140:143], v[6:7], off
	v_lshl_add_u64 v[2:3], v[200:201], 1, v[2:3]
	v_lshl_add_u64 v[4:5], v[202:203], 0, s[62:63]
	v_lshl_add_u64 v[6:7], v[4:5], 0, v[204:205]
	global_load_dwordx4 v[144:147], v[2:3], off
	global_load_dwordx4 v[148:151], v[6:7], off
	v_lshl_add_u64 v[2:3], v[4:5], 0, v[210:211]
	global_load_dwordx4 v[152:155], v[2:3], off
	v_add_u32_e32 v0, 0xffffffa1, v224
	v_cmp_le_i32_e32 vcc, v0, v213
	s_and_saveexec_b64 s[38:39], vcc
	s_cbranch_execz .LBB0_650
	s_nop 0
	ds_read_b128 v[2:5], v228
	ds_read_b128 v[230:233], v228 offset:32
	ds_read_b128 v[234:237], v228 offset:64
	ds_read_b128 v[246:249], v228 offset:96
	ds_read_b128 v[250:253], v228 offset:128
	s_waitcnt lgkmcnt(4)
	v_mfma_f32_32x32x16_bf16 v[80:95], v[2:5], v[96:99], 0
	ds_read_b128 v[2:5], v228 offset:160
	s_waitcnt lgkmcnt(4)
	v_mfma_f32_32x32x16_bf16 v[80:95], v[230:233], v[100:103], v[80:95]
	ds_read_b128 v[230:233], v228 offset:192
	s_waitcnt lgkmcnt(4)
	v_mfma_f32_32x32x16_bf16 v[80:95], v[234:237], v[104:107], v[80:95]
	ds_read_b128 v[234:237], v228 offset:224
	s_waitcnt lgkmcnt(4)
	v_mfma_f32_32x32x16_bf16 v[80:95], v[246:249], v[108:111], v[80:95]
	ds_read_b128 v[246:249], v228 offset:256
	s_waitcnt lgkmcnt(4)
	v_mfma_f32_32x32x16_bf16 v[80:95], v[250:253], v[112:115], v[80:95]
	ds_read_b128 v[250:253], v228 offset:288
	s_waitcnt lgkmcnt(4)
	v_mfma_f32_32x32x16_bf16 v[80:95], v[2:5], v[116:119], v[80:95]
	ds_read_b128 v[2:5], v228 offset:320
	s_waitcnt lgkmcnt(4)
	v_mfma_f32_32x32x16_bf16 v[80:95], v[230:233], v[120:123], v[80:95]
	ds_read_b128 v[230:233], v228 offset:352
	s_waitcnt lgkmcnt(4)
	v_mfma_f32_32x32x16_bf16 v[80:95], v[234:237], v[124:127], v[80:95]
	s_waitcnt lgkmcnt(3)
	v_mfma_f32_32x32x16_bf16 v[80:95], v[246:249], v[128:131], v[80:95]
	s_waitcnt lgkmcnt(2)
	v_mfma_f32_32x32x16_bf16 v[80:95], v[250:253], v[176:179], v[80:95]
	s_waitcnt lgkmcnt(1)
	v_mfma_f32_32x32x16_bf16 v[80:95], v[2:5], v[132:135], v[80:95]
	s_waitcnt lgkmcnt(0)
	v_mfma_f32_32x32x16_bf16 v[80:95], v[230:233], v[180:183], v[80:95]
	s_nop 0
	v_subrev_u32_e32 v0, 64, v224
	v_cmp_gt_i32_e32 vcc, v0, v213
	s_and_saveexec_b64 s[78:79], vcc
	s_cbranch_execz .LBB0_647
	v_add_u32_e32 v0, 64, v225
	s_nop 0
	v_cmp_gt_i32_e64 s[30:31], 26, v0
	v_cmp_gt_i32_e64 s[34:35], 27, v0
	v_cmp_gt_i32_e64 s[28:29], 25, v0
	s_and_b64 s[30:31], s[34:35], s[30:31]
	v_cmp_gt_i32_e64 s[26:27], 24, v0
	s_and_b64 s[28:29], s[30:31], s[28:29]
	v_cmp_gt_i32_e64 s[24:25], 19, v0
	s_and_b64 s[26:27], s[28:29], s[26:27]
	v_cmp_gt_i32_e64 s[22:23], 18, v0
	s_and_b64 s[24:25], s[26:27], s[24:25]
	v_cmp_gt_i32_e64 s[20:21], 17, v0
	s_and_b64 s[22:23], s[24:25], s[22:23]
	v_cmp_gt_i32_e64 s[18:19], 16, v0
	s_and_b64 s[20:21], s[22:23], s[20:21]
	v_cmp_gt_i32_e64 s[16:17], 11, v0
	s_and_b64 s[18:19], s[20:21], s[18:19]
	v_cmp_gt_i32_e64 s[14:15], 10, v0
	s_and_b64 s[16:17], s[18:19], s[16:17]
	v_cmp_gt_i32_e64 s[12:13], 9, v0
	s_and_b64 s[14:15], s[16:17], s[14:15]
	v_cmp_gt_i32_e64 s[10:11], 8, v0
	s_and_b64 s[12:13], s[14:15], s[12:13]
	v_cmp_gt_i32_e64 s[8:9], 3, v0
	s_and_b64 s[10:11], s[12:13], s[10:11]
	v_cmp_gt_i32_e64 s[4:5], 2, v0
	s_and_b64 s[8:9], s[10:11], s[8:9]
	v_cmp_gt_i32_e64 s[2:3], 1, v0
	s_and_b64 s[4:5], s[8:9], s[4:5]
	v_cmp_gt_i32_e32 vcc, 0, v0
	s_and_b64 s[2:3], s[4:5], s[2:3]
	s_and_b64 vcc, s[2:3], vcc
	v_cndmask_b32_e64 v95, v95, v244, s[34:35]
	v_cndmask_b32_e64 v94, v94, v244, s[30:31]
	v_cndmask_b32_e64 v93, v93, v244, s[28:29]
	v_cndmask_b32_e64 v92, v92, v244, s[26:27]
	v_cndmask_b32_e64 v91, v91, v244, s[24:25]
	v_cndmask_b32_e64 v90, v90, v244, s[22:23]
	v_cndmask_b32_e64 v89, v89, v244, s[20:21]
	v_cndmask_b32_e64 v88, v88, v244, s[18:19]
	v_cndmask_b32_e64 v87, v87, v244, s[16:17]
	v_cndmask_b32_e64 v86, v86, v244, s[14:15]
	v_cndmask_b32_e64 v85, v85, v244, s[12:13]
	v_cndmask_b32_e64 v84, v84, v244, s[10:11]
	v_cndmask_b32_e64 v83, v83, v244, s[8:9]
	v_cndmask_b32_e64 v82, v82, v244, s[4:5]
	v_cndmask_b32_e64 v81, v81, v244, s[2:3]
	v_cndmask_b32_e32 v80, v80, v244, vcc

.LBB0_649:
	v_sub_f32_e32 v3, v80, v2
	v_exp_f32_e32 v3, v3
	v_sub_f32_e32 v4, v81, v2
	v_exp_f32_e32 v4, v4
	v_sub_f32_e32 v5, v82, v2
	v_exp_f32_e32 v5, v5
	v_sub_f32_e32 v6, v83, v2
	v_exp_f32_e32 v6, v6
	v_sub_f32_e32 v8, v84, v2
	v_add_f32_e32 v7, 0, v3
	v_exp_f32_e32 v8, v8
	v_sub_f32_e32 v9, v85, v2
	v_add_f32_e32 v7, v4, v7
	v_exp_f32_e32 v9, v9
	v_sub_f32_e32 v10, v86, v2
	v_add_f32_e32 v7, v5, v7
	v_exp_f32_e32 v10, v10
	v_sub_f32_e32 v11, v87, v2
	v_add_f32_e32 v7, v6, v7
	v_exp_f32_e32 v11, v11
	v_sub_f32_e32 v12, v88, v2
	v_add_f32_e32 v7, v8, v7
	v_exp_f32_e32 v12, v12
	v_sub_f32_e32 v13, v89, v2
	v_add_f32_e32 v7, v9, v7
	v_exp_f32_e32 v13, v13
	v_sub_f32_e32 v14, v90, v2
	v_add_f32_e32 v7, v10, v7
	v_exp_f32_e32 v14, v14
	v_sub_f32_e32 v15, v91, v2
	v_add_f32_e32 v7, v11, v7
	v_exp_f32_e32 v15, v15
	v_sub_f32_e32 v80, v92, v2
	v_add_f32_e32 v7, v12, v7
	v_exp_f32_e32 v80, v80
	v_sub_f32_e32 v81, v93, v2
	v_add_f32_e32 v7, v13, v7
	v_exp_f32_e32 v81, v81
	v_sub_f32_e32 v82, v94, v2
	v_add_f32_e32 v7, v14, v7
	v_exp_f32_e32 v82, v82
	v_sub_f32_e32 v83, v95, v2
	v_add_f32_e32 v7, v15, v7
	v_exp_f32_e32 v83, v83
	v_add_f32_e32 v7, v80, v7
	v_add_f32_e32 v7, v81, v7
	v_add_f32_e32 v7, v82, v7
	v_add_f32_e32 v84, v83, v7
	v_fmac_f32_e32 v84, v212, v0
	v_cvt_pk_bf16_f32 v4, v3, v4
	v_cvt_pk_bf16_f32 v5, v5, v6
	v_cvt_pk_bf16_f32 v6, v8, v9
	v_cvt_pk_bf16_f32 v7, v10, v11
	v_cvt_pk_bf16_f32 v8, v12, v13
	v_cvt_pk_bf16_f32 v9, v14, v15
	v_cvt_pk_bf16_f32 v10, v80, v81
	v_cvt_pk_bf16_f32 v11, v82, v83
	s_nop 0
	v_add_u32_e32 v0, v223, v222
	ds_read_b64 v[12:13], v0 offset:25600
	ds_read_b64 v[14:15], v0 offset:25616
	ds_read_b64 v[230:231], v0 offset:25632
	ds_read_b64 v[232:233], v0 offset:25648
	ds_read_b64 v[234:235], v0 offset:30208
	ds_read_b64 v[236:237], v0 offset:30224
	ds_read_b64 v[246:247], v0 offset:30240
	ds_read_b64 v[248:249], v0 offset:30256
	ds_read_b64 v[250:251], v0 offset:34816
	ds_read_b64 v[252:253], v0 offset:34832
	s_waitcnt lgkmcnt(8)
	v_mfma_f32_32x32x16_bf16 v[64:79], v[12:15], v[4:7], v[64:79]
	ds_read_b64 v[12:13], v0 offset:34848
	ds_read_b64 v[14:15], v0 offset:34864
	s_waitcnt lgkmcnt(8)
	v_mfma_f32_32x32x16_bf16 v[64:79], v[230:233], v[8:11], v[64:79]
	ds_read_b64 v[230:231], v0 offset:39424
	ds_read_b64 v[232:233], v0 offset:39440
	s_waitcnt lgkmcnt(8)
	v_mfma_f32_32x32x16_bf16 v[48:63], v[234:237], v[4:7], v[48:63]
	ds_read_b64 v[234:235], v0 offset:39456
	ds_read_b64 v[236:237], v0 offset:39472
	s_waitcnt lgkmcnt(8)
	v_mfma_f32_32x32x16_bf16 v[48:63], v[246:249], v[8:11], v[48:63]
	s_waitcnt lgkmcnt(6)
	v_mfma_f32_32x32x16_bf16 v[32:47], v[250:253], v[4:7], v[32:47]
	s_waitcnt lgkmcnt(4)
	v_mfma_f32_32x32x16_bf16 v[32:47], v[12:15], v[8:11], v[32:47]
	s_waitcnt lgkmcnt(2)
	v_mfma_f32_32x32x16_bf16 v[16:31], v[230:233], v[4:7], v[16:31]
	s_waitcnt lgkmcnt(0)
	v_mfma_f32_32x32x16_bf16 v[16:31], v[234:237], v[8:11], v[16:31]
	s_nop 0
	v_mov_b32_e32 v229, v2
	v_mov_b32_e32 v212, v84
; #define AT_LOAD(RK, RV, T) { const size_t ko_ = (size_t)(T) * 64 * 192; const int vo_ = (T) * 64; \
;     _Pragma("unroll") for (int i = 0; i < 3; ++i) { const int id = tid + NT * i, row = id / 24, cc = id % 24; RK[i] = *(const u32x4*)(Kg + ko_ + row * 192 + cc * 8); } \
;     _Pragma("unroll") for (int i = 0; i < 2; ++i) RV[i] = *(const u32x4*)(Vg + (size_t)(vrow + 64 * i) * S_ + vo_ + vcc * 8); }
; #define AT_WRITE(RK, RV, ST) { char* dK = smem + (ST) * STG; \
;     _Pragma("unroll") for (int i = 0; i < 3; ++i) { const int id = tid + NT * i, row = id / 24, cc = id % 24; *(u32x4*)(dK + row * 400 + cc * 16) = RK[i]; } \
;     _Pragma("unroll") for (int i = 0; i < 2; ++i) *(u32x4*)(dK + KST + (vrow + 64 * i) * 144 + vcc * 16) = RV[i]; }
; DI void mla_attn_item(const Params& P, int hd, int b, char* smem) {
;     ...
;     AT_WRITE(rk1, rv1, 1);
;     AT_LOAD(rk1, rv1, (kt + 3 < ntl ? kt + 3 : ntl));
;     AT_COMPUTE(0, kt);
;     __syncthreads();
;     AT_WRITE(rk0, rv0, 0);
;     AT_LOAD(rk0, rv0, (kt + 4 < ntl ? kt + 4 : ntl));
;     AT_COMPUTE(1, kt + 1);
.LBB0_650:
	s_or_b64 exec, exec, s[38:39]
	s_add_i32 s2, s60, 6
	s_min_u32 s2, s2, s57
	s_mul_i32 s62, s2, 0x6000
	v_lshl_add_u64 v[2:3], v[188:189], 0, s[62:63]
	v_lshl_add_u64 v[4:5], v[190:191], 1, v[2:3]
	s_waitcnt lgkmcnt(0)
	s_barrier
	s_waitcnt vmcnt(5)
	ds_write_b128 v217, v[156:159]
	ds_write_b128 v218, v[160:163]
	ds_write_b128 v219, v[164:167]
	ds_write_b128 v220, v[168:171] offset:25600
	ds_write_b128 v220, v[172:175] offset:34816
	v_lshl_add_u64 v[4:5], v[192:193], 1, v[4:5]
	v_lshl_add_u64 v[6:7], v[194:195], 1, v[2:3]
	v_lshl_add_u64 v[2:3], v[198:199], 1, v[2:3]
	s_lshl_b32 s62, s2, 7
	v_lshl_add_u64 v[6:7], v[196:197], 1, v[6:7]
	global_load_dwordx4 v[156:159], v[4:5], off
	global_load_dwordx4 v[160:163], v[6:7], off
	v_lshl_add_u64 v[2:3], v[200:201], 1, v[2:3]
	v_lshl_add_u64 v[4:5], v[202:203], 0, s[62:63]
	v_lshl_add_u64 v[6:7], v[4:5], 0, v[204:205]
	global_load_dwordx4 v[164:167], v[2:3], off
	global_load_dwordx4 v[168:171], v[6:7], off
	v_lshl_add_u64 v[2:3], v[4:5], 0, v[210:211]
	global_load_dwordx4 v[172:175], v[2:3], off
	v_subrev_u32_e32 v0, 31, v224
	v_cmp_le_i32_e32 vcc, v0, v213
	s_and_saveexec_b64 s[38:39], vcc
	s_cbranch_execz .LBB0_643
	s_nop 0
	ds_read_b128 v[2:5], v228 offset:44032
	ds_read_b128 v[230:233], v228 offset:44064
	ds_read_b128 v[234:237], v228 offset:44096
	ds_read_b128 v[246:249], v228 offset:44128
	ds_read_b128 v[250:253], v228 offset:44160
	s_waitcnt lgkmcnt(4)
	v_mfma_f32_32x32x16_bf16 v[80:95], v[2:5], v[96:99], 0
	ds_read_b128 v[2:5], v228 offset:44192
	s_waitcnt lgkmcnt(4)
	v_mfma_f32_32x32x16_bf16 v[80:95], v[230:233], v[100:103], v[80:95]
	ds_read_b128 v[230:233], v228 offset:44224
	s_waitcnt lgkmcnt(4)
	v_mfma_f32_32x32x16_bf16 v[80:95], v[234:237], v[104:107], v[80:95]
	ds_read_b128 v[234:237], v228 offset:44256
	s_waitcnt lgkmcnt(4)
	v_mfma_f32_32x32x16_bf16 v[80:95], v[246:249], v[108:111], v[80:95]
	ds_read_b128 v[246:249], v228 offset:44288
	s_waitcnt lgkmcnt(4)
	v_mfma_f32_32x32x16_bf16 v[80:95], v[250:253], v[112:115], v[80:95]
	ds_read_b128 v[250:253], v228 offset:44320
	s_waitcnt lgkmcnt(4)
	v_mfma_f32_32x32x16_bf16 v[80:95], v[2:5], v[116:119], v[80:95]
	ds_read_b128 v[2:5], v228 offset:44352
	s_waitcnt lgkmcnt(4)
	v_mfma_f32_32x32x16_bf16 v[80:95], v[230:233], v[120:123], v[80:95]
	ds_read_b128 v[230:233], v228 offset:44384
	s_waitcnt lgkmcnt(4)
	v_mfma_f32_32x32x16_bf16 v[80:95], v[234:237], v[124:127], v[80:95]
	s_waitcnt lgkmcnt(3)
	v_mfma_f32_32x32x16_bf16 v[80:95], v[246:249], v[128:131], v[80:95]
	s_waitcnt lgkmcnt(2)
	v_mfma_f32_32x32x16_bf16 v[80:95], v[250:253], v[176:179], v[80:95]
	s_waitcnt lgkmcnt(1)
	v_mfma_f32_32x32x16_bf16 v[80:95], v[2:5], v[132:135], v[80:95]
	s_waitcnt lgkmcnt(0)
	v_mfma_f32_32x32x16_bf16 v[80:95], v[230:233], v[180:183], v[80:95]
	s_nop 0
	v_cmp_gt_i32_e32 vcc, v224, v213
	s_and_saveexec_b64 s[78:79], vcc
	s_cbranch_execz .LBB0_653
	v_mov_b32_e32 v0, v225
	s_nop 0
	v_cmp_gt_i32_e64 s[30:31], 26, v0
	v_cmp_gt_i32_e64 s[34:35], 27, v0
	v_cmp_gt_i32_e64 s[28:29], 25, v0
	s_and_b64 s[30:31], s[34:35], s[30:31]
	v_cmp_gt_i32_e64 s[26:27], 24, v0
	s_and_b64 s[28:29], s[30:31], s[28:29]
	v_cmp_gt_i32_e64 s[24:25], 19, v0
	s_and_b64 s[26:27], s[28:29], s[26:27]
	v_cmp_gt_i32_e64 s[22:23], 18, v0
	s_and_b64 s[24:25], s[26:27], s[24:25]
	v_cmp_gt_i32_e64 s[20:21], 17, v0
	s_and_b64 s[22:23], s[24:25], s[22:23]
	v_cmp_gt_i32_e64 s[18:19], 16, v0
	s_and_b64 s[20:21], s[22:23], s[20:21]
	v_cmp_gt_i32_e64 s[16:17], 11, v0
	s_and_b64 s[18:19], s[20:21], s[18:19]
	v_cmp_gt_i32_e64 s[14:15], 10, v0
	s_and_b64 s[16:17], s[18:19], s[16:17]
	v_cmp_gt_i32_e64 s[12:13], 9, v0
	s_and_b64 s[14:15], s[16:17], s[14:15]
	v_cmp_gt_i32_e64 s[10:11], 8, v0
	s_and_b64 s[12:13], s[14:15], s[12:13]
	v_cmp_gt_i32_e64 s[8:9], 3, v0
	s_and_b64 s[10:11], s[12:13], s[10:11]
	v_cmp_gt_i32_e64 s[4:5], 2, v0
	s_and_b64 s[8:9], s[10:11], s[8:9]
	v_cmp_gt_i32_e64 s[2:3], 1, v0
	s_and_b64 s[4:5], s[8:9], s[4:5]
	v_cmp_gt_i32_e32 vcc, 0, v0
	s_and_b64 s[2:3], s[4:5], s[2:3]
	s_and_b64 vcc, s[2:3], vcc
	v_cndmask_b32_e64 v95, v95, v244, s[34:35]
	v_cndmask_b32_e64 v94, v94, v244, s[30:31]
	v_cndmask_b32_e64 v93, v93, v244, s[28:29]
	v_cndmask_b32_e64 v92, v92, v244, s[26:27]
	v_cndmask_b32_e64 v91, v91, v244, s[24:25]
	v_cndmask_b32_e64 v90, v90, v244, s[22:23]
	v_cndmask_b32_e64 v89, v89, v244, s[20:21]
	v_cndmask_b32_e64 v88, v88, v244, s[18:19]
	v_cndmask_b32_e64 v87, v87, v244, s[16:17]
	v_cndmask_b32_e64 v86, v86, v244, s[14:15]
	v_cndmask_b32_e64 v85, v85, v244, s[12:13]
	v_cndmask_b32_e64 v84, v84, v244, s[10:11]
	v_cndmask_b32_e64 v83, v83, v244, s[8:9]
	v_cndmask_b32_e64 v82, v82, v244, s[4:5]
	v_cndmask_b32_e64 v81, v81, v244, s[2:3]
	v_cndmask_b32_e32 v80, v80, v244, vcc

; #define PG8_STAGE(bufoff, gbase, voff) do { _Pragma("unroll") for (int _i = 0; _i < 2; ++_i) \
;         __builtin_amdgcn_global_load_lds((const unsigned*)((const char*)(gbase) + (voff)[_i]), (PG8_LAS unsigned*)(lds + (bufoff) + ldsw + _i * 8192), 16, 0, 0); } while (0)
; #define PG8_LDA(dst, b, h) do { _Pragma("unroll") for (int m = 0; m < 4; ++m) _Pragma("unroll") for (int k = 0; k < 2; ++k) dst[m][k] = *(const PG8_LAS bf16x8*)(lds + PG8_SA(b, h) + aoff + m * 2048 + k * 1024); } while (0)
; #define PG8_LDB(dst, b, h) do { _Pragma("unroll") for (int n = 0; n < 2; ++n) _Pragma("unroll") for (int k = 0; k < 2; ++k) dst[n][k] = *(const PG8_LAS bf16x8*)(lds + PG8_SB(b, h) + boff + n * 2048 + k * 1024); } while (0)
; #define PG8_MMA(ai, bj, At, Bt) do { __builtin_amdgcn_s_setprio(1); _Pragma("unroll") for (int m = 0; m < 4; ++m) _Pragma("unroll") for (int n = 0; n < 2; ++n) _Pragma("unroll") for (int k = 0; k < 2; ++k) \
;         acc[ai][bj][m][n] = __builtin_amdgcn_mfma_f32_16x16x32_bf16(Bt[n][k], At[m][k], acc[ai][bj][m][n], 0, 0, 0); __builtin_amdgcn_s_setprio(0); } while (0)
; #define PG8_WAIT_V(n) asm volatile("s_waitcnt vmcnt(" #n ")" ::: "memory")
; template <class Epi, class Sched, bool ALIGN_EPI = false, bool SP2 = false>
; __device__ __forceinline__ void gemm_phase(PG8_LAS unsigned char* lds, const Gemm g, const Sched& S, const Epi& E) {
;     ...
;             PG8_LDB(B0, 0, 0); PG8_LDB(B1, 0, 1); PG8_SCHED; PG8_LDA(At, 0, 0); PG8_STAGE(PG8_SA(1, 1), a1 + hstep, voffA);
;             PG8_WAIT_V(8); PG8_WAIT_L(0); PG8_BAR; PG8_MMA(0, 0, At, B0); PG8_MMA(0, 1, At, B1); PG8_BAR; PG8_SCHED;
;             PG8_LDA(At, 0, 1); PG8_STAGE(PG8_SB(0, 0), b2, voffB); PG8_STAGE(PG8_SB(0, 1), b2 + hstep, voffB); PG8_STAGE(PG8_SA(0, 0), a2, voffA);
;             PG8_WAIT_V(8); PG8_WAIT_L(0); PG8_BAR; PG8_MMA(1, 0, At, B0); PG8_MMA(1, 1, At, B1); PG8_BAR; PG8_SCHED;
;             PG8_LDB(B0, 1, 0); PG8_LDB(B1, 1, 1); PG8_SCHED; PG8_LDA(At, 1, 0); PG8_STAGE(PG8_SA(0, 1), a2 + hstep, voffA);
;             PG8_WAIT_V(8); PG8_WAIT_L(0); PG8_BAR; PG8_MMA(0, 0, At, B0); PG8_MMA(0, 1, At, B1); PG8_BAR; PG8_SCHED;
;             PG8_LDA(At, 1, 1); PG8_STAGE(PG8_SB(1, 0), b3, voffB); PG8_STAGE(PG8_SB(1, 1), b3 + hstep, voffB); PG8_STAGE(PG8_SA(1, 0), a3, voffA);
;             PG8_WAIT_V(8); PG8_WAIT_L(0); PG8_BAR; PG8_MMA(1, 0, At, B0); PG8_MMA(1, 1, At, B1); PG8_BAR; PG8_SCHED;
.LBB0_825:
	v_or_b32_e32 v159, 0x10000, v157
	v_add_u32_e32 v164, 0x10400, v157
	ds_read_b128 v[160:163], v159
	ds_read_b128 v[164:167], v164
	v_add_u32_e32 v159, 0x10800, v157
	v_add_u32_e32 v172, 0x10c00, v157
	s_add_u32 s20, s18, 0x100
	ds_read_b128 v[168:171], v159
	ds_read_b128 v[172:175], v172
	v_or_b32_e32 v159, 0x14000, v157
	v_add_u32_e32 v180, 0x14400, v157
	s_addc_u32 s21, s19, 0
	ds_read_b128 v[176:179], v159
	ds_read_b128 v[180:183], v180
	v_add_u32_e32 v159, 0x14800, v157
	v_add_u32_e32 v188, 0x14c00, v157
	s_add_u32 s22, s10, s18
	ds_read_b128 v[184:187], v159
	ds_read_b128 v[188:191], v188
	s_addc_u32 s23, s11, s19
	s_cmp_eq_u32 s96, 28
	s_cselect_b32 s24, 0, s20
	s_cselect_b32 s25, 0, s21
	s_cselect_b32 s22, s79, s22
	s_cselect_b32 s23, s13, s23
	s_add_u32 s24, s70, s24
	s_addc_u32 s25, s71, s25
	v_lshl_add_u64 v[204:205], v[152:153], 0, s[18:19]
	s_add_i32 m0, s26, 0xc000
	ds_read_b128 v[192:195], v156
	ds_read_b128 v[196:199], v156 offset:1024
	ds_read_b128 v[200:203], v156 offset:2048
	ds_read_b128 v[210:213], v156 offset:3072
	ds_read_b128 v[214:217], v156 offset:4096
	ds_read_b128 v[218:221], v156 offset:5120
	ds_read_b128 v[222:225], v156 offset:6144
	ds_read_b128 v[226:229], v156 offset:7168
	global_load_lds_dwordx4 v[204:205], off
	v_lshl_add_u64 v[204:205], v[154:155], 0, s[18:19]
	s_add_i32 m0, s26, 0xe000
	s_nop 0
	global_load_lds_dwordx4 v[204:205], off
	s_waitcnt vmcnt(8)
	s_waitcnt lgkmcnt(0)
	s_barrier
	s_nop 0
	s_waitcnt lgkmcnt(0)
	v_mfma_f32_16x16x32_bf16 v[126:129], v[160:163], v[192:195], v[126:129]
	v_mfma_f32_16x16x32_bf16 v[122:125], v[168:171], v[192:195], v[122:125]
	v_mfma_f32_16x16x32_bf16 v[118:121], v[160:163], v[200:203], v[118:121]
	v_mfma_f32_16x16x32_bf16 v[114:117], v[168:171], v[200:203], v[114:117]
	v_mfma_f32_16x16x32_bf16 v[102:105], v[160:163], v[214:217], v[102:105]
	v_mfma_f32_16x16x32_bf16 v[98:101], v[168:171], v[214:217], v[98:101]
	v_mfma_f32_16x16x32_bf16 v[86:89], v[160:163], v[222:225], v[86:89]
	v_mfma_f32_16x16x32_bf16 v[82:85], v[168:171], v[222:225], v[82:85]
	v_mfma_f32_16x16x32_bf16 v[126:129], v[164:167], v[196:199], v[126:129]
	v_mfma_f32_16x16x32_bf16 v[122:125], v[172:175], v[196:199], v[122:125]
	v_mfma_f32_16x16x32_bf16 v[118:121], v[164:167], v[210:213], v[118:121]
	v_mfma_f32_16x16x32_bf16 v[114:117], v[172:175], v[210:213], v[114:117]
	v_mfma_f32_16x16x32_bf16 v[102:105], v[164:167], v[218:221], v[102:105]
	v_mfma_f32_16x16x32_bf16 v[98:101], v[172:175], v[218:221], v[98:101]
	v_mfma_f32_16x16x32_bf16 v[86:89], v[164:167], v[226:229], v[86:89]
	v_mfma_f32_16x16x32_bf16 v[82:85], v[172:175], v[226:229], v[82:85]
	s_nop 0
	s_nop 0
	v_mfma_f32_16x16x32_bf16 v[110:113], v[176:179], v[192:195], v[110:113]
	v_mfma_f32_16x16x32_bf16 v[106:109], v[184:187], v[192:195], v[106:109]
	v_mfma_f32_16x16x32_bf16 v[94:97], v[176:179], v[200:203], v[94:97]
	v_mfma_f32_16x16x32_bf16 v[90:93], v[184:187], v[200:203], v[90:93]
	v_mfma_f32_16x16x32_bf16 v[78:81], v[176:179], v[214:217], v[78:81]
	v_mfma_f32_16x16x32_bf16 v[74:77], v[184:187], v[214:217], v[74:77]
	v_mfma_f32_16x16x32_bf16 v[70:73], v[176:179], v[222:225], v[70:73]
	v_mfma_f32_16x16x32_bf16 v[66:69], v[184:187], v[222:225], v[66:69]
	v_mfma_f32_16x16x32_bf16 v[110:113], v[180:183], v[196:199], v[110:113]
	v_mfma_f32_16x16x32_bf16 v[106:109], v[188:191], v[196:199], v[106:109]
	v_mfma_f32_16x16x32_bf16 v[94:97], v[180:183], v[210:213], v[94:97]
	v_mfma_f32_16x16x32_bf16 v[90:93], v[188:191], v[210:213], v[90:93]
	v_mfma_f32_16x16x32_bf16 v[78:81], v[180:183], v[218:221], v[78:81]
	v_mfma_f32_16x16x32_bf16 v[74:77], v[188:191], v[218:221], v[74:77]
	v_mfma_f32_16x16x32_bf16 v[70:73], v[180:183], v[226:229], v[70:73]
	v_mfma_f32_16x16x32_bf16 v[66:69], v[188:191], v[226:229], v[66:69]
	s_nop 0
	s_barrier
	s_mov_b32 m0, s27
	v_lshl_add_u64 v[204:205], s[22:23], 0, v[0:1]
	s_add_u32 s18, s22, 0x80000
	ds_read_b128 v[192:195], v156 offset:16384
	ds_read_b128 v[196:199], v156 offset:17408
	ds_read_b128 v[200:203], v156 offset:18432
	ds_read_b128 v[210:213], v156 offset:19456
	ds_read_b128 v[214:217], v156 offset:20480
	ds_read_b128 v[218:221], v156 offset:21504
	ds_read_b128 v[222:225], v156 offset:22528
	ds_read_b128 v[226:229], v156 offset:23552
	global_load_lds_dwordx4 v[204:205], off
	v_lshl_add_u64 v[230:231], s[22:23], 0, v[130:131]
	s_mov_b32 m0, s28
	s_addc_u32 s19, s23, 0
	global_load_lds_dwordx4 v[230:231], off
	v_lshl_add_u64 v[232:233], s[18:19], 0, v[0:1]
	s_mov_b32 m0, s29
	v_lshl_add_u64 v[234:235], s[24:25], 0, v[132:133]
	global_load_lds_dwordx4 v[232:233], off
	v_lshl_add_u64 v[232:233], s[18:19], 0, v[130:131]
	s_mov_b32 m0, s30
	s_nop 0
	global_load_lds_dwordx4 v[232:233], off
	v_lshl_add_u64 v[232:233], s[24:25], 0, v[134:135]
	s_mov_b32 m0, s26
	s_nop 0
	global_load_lds_dwordx4 v[232:233], off
	s_mov_b32 m0, s31
	s_nop 0
	global_load_lds_dwordx4 v[234:235], off
	s_waitcnt vmcnt(8)
	s_waitcnt lgkmcnt(0)
	s_barrier
; #define PG8_STAGE(bufoff, gbase, voff) do { _Pragma("unroll") for (int _i = 0; _i < 2; ++_i) \
;         __builtin_amdgcn_global_load_lds((const unsigned*)((const char*)(gbase) + (voff)[_i]), (PG8_LAS unsigned*)(lds + (bufoff) + ldsw + _i * 8192), 16, 0, 0); } while (0)
; #define PG8_LDA(dst, b, h) do { _Pragma("unroll") for (int m = 0; m < 4; ++m) _Pragma("unroll") for (int k = 0; k < 2; ++k) dst[m][k] = *(const PG8_LAS bf16x8*)(lds + PG8_SA(b, h) + aoff + m * 2048 + k * 1024); } while (0)
; #define PG8_LDB(dst, b, h) do { _Pragma("unroll") for (int n = 0; n < 2; ++n) _Pragma("unroll") for (int k = 0; k < 2; ++k) dst[n][k] = *(const PG8_LAS bf16x8*)(lds + PG8_SB(b, h) + boff + n * 2048 + k * 1024); } while (0)
; #define PG8_MMA(ai, bj, At, Bt) do { __builtin_amdgcn_s_setprio(1); _Pragma("unroll") for (int m = 0; m < 4; ++m) _Pragma("unroll") for (int n = 0; n < 2; ++n) _Pragma("unroll") for (int k = 0; k < 2; ++k) \
;         acc[ai][bj][m][n] = __builtin_amdgcn_mfma_f32_16x16x32_bf16(Bt[n][k], At[m][k], acc[ai][bj][m][n], 0, 0, 0); __builtin_amdgcn_s_setprio(0); } while (0)
; #define PG8_WAIT_V(n) asm volatile("s_waitcnt vmcnt(" #n ")" ::: "memory")
; template <class Epi, class Sched, bool ALIGN_EPI = false, bool SP2 = false>
; __device__ __forceinline__ void gemm_phase(PG8_LAS unsigned char* lds, const Gemm g, const Sched& S, const Epi& E) {
;     ...
;             PG8_LDB(B0, 0, 0); PG8_LDB(B1, 0, 1); PG8_SCHED; PG8_LDA(At, 0, 0); PG8_STAGE(PG8_SA(1, 1), a1 + hstep, voffA);
;             PG8_WAIT_V(8); PG8_WAIT_L(0); PG8_BAR; PG8_MMA(0, 0, At, B0); PG8_MMA(0, 1, At, B1); PG8_BAR; PG8_SCHED;
;             PG8_LDA(At, 0, 1); PG8_STAGE(PG8_SB(0, 0), b2, voffB); PG8_STAGE(PG8_SB(0, 1), b2 + hstep, voffB); PG8_STAGE(PG8_SA(0, 0), a2, voffA);
;             PG8_WAIT_V(8); PG8_WAIT_L(0); PG8_BAR; PG8_MMA(1, 0, At, B0); PG8_MMA(1, 1, At, B1); PG8_BAR; PG8_SCHED;
;             PG8_LDB(B0, 1, 0); PG8_LDB(B1, 1, 1); PG8_SCHED; PG8_LDA(At, 1, 0); PG8_STAGE(PG8_SA(0, 1), a2 + hstep, voffA);
;             PG8_WAIT_V(8); PG8_WAIT_L(0); PG8_BAR; PG8_MMA(0, 0, At, B0); PG8_MMA(0, 1, At, B1); PG8_BAR; PG8_SCHED;
;             PG8_LDA(At, 1, 1); PG8_STAGE(PG8_SB(1, 0), b3, voffB); PG8_STAGE(PG8_SB(1, 1), b3 + hstep, voffB); PG8_STAGE(PG8_SA(1, 0), a3, voffA);
;             PG8_WAIT_V(8); PG8_WAIT_L(0); PG8_BAR; PG8_MMA(1, 0, At, B0); PG8_MMA(1, 1, At, B1); PG8_BAR; PG8_SCHED;
	s_nop 0
	s_waitcnt lgkmcnt(0)
	v_mfma_f32_16x16x32_bf16 v[62:65], v[160:163], v[192:195], v[62:65]
	v_mfma_f32_16x16x32_bf16 v[58:61], v[168:171], v[192:195], v[58:61]
	v_mfma_f32_16x16x32_bf16 v[54:57], v[160:163], v[200:203], v[54:57]
	v_mfma_f32_16x16x32_bf16 v[50:53], v[168:171], v[200:203], v[50:53]
	v_mfma_f32_16x16x32_bf16 v[38:41], v[160:163], v[214:217], v[38:41]
	v_mfma_f32_16x16x32_bf16 v[34:37], v[168:171], v[214:217], v[34:37]
	v_mfma_f32_16x16x32_bf16 v[22:25], v[160:163], v[222:225], v[22:25]
	v_mfma_f32_16x16x32_bf16 v[18:21], v[168:171], v[222:225], v[18:21]
	v_mfma_f32_16x16x32_bf16 v[62:65], v[164:167], v[196:199], v[62:65]
	v_mfma_f32_16x16x32_bf16 v[58:61], v[172:175], v[196:199], v[58:61]
	v_mfma_f32_16x16x32_bf16 v[54:57], v[164:167], v[210:213], v[54:57]
	v_mfma_f32_16x16x32_bf16 v[50:53], v[172:175], v[210:213], v[50:53]
	v_mfma_f32_16x16x32_bf16 v[38:41], v[164:167], v[218:221], v[38:41]
	v_mfma_f32_16x16x32_bf16 v[34:37], v[172:175], v[218:221], v[34:37]
	v_mfma_f32_16x16x32_bf16 v[22:25], v[164:167], v[226:229], v[22:25]
	v_mfma_f32_16x16x32_bf16 v[18:21], v[172:175], v[226:229], v[18:21]
	s_nop 0
	s_nop 0
	v_mfma_f32_16x16x32_bf16 v[46:49], v[176:179], v[192:195], v[46:49]
	v_mfma_f32_16x16x32_bf16 v[42:45], v[184:187], v[192:195], v[42:45]
	v_mfma_f32_16x16x32_bf16 v[30:33], v[176:179], v[200:203], v[30:33]
	v_mfma_f32_16x16x32_bf16 v[26:29], v[184:187], v[200:203], v[26:29]
	v_mfma_f32_16x16x32_bf16 v[14:17], v[176:179], v[214:217], v[14:17]
	v_mfma_f32_16x16x32_bf16 v[10:13], v[184:187], v[214:217], v[10:13]
	v_mfma_f32_16x16x32_bf16 v[6:9], v[176:179], v[222:225], v[6:9]
	v_mfma_f32_16x16x32_bf16 v[2:5], v[184:187], v[222:225], v[2:5]
	v_mfma_f32_16x16x32_bf16 v[46:49], v[180:183], v[196:199], v[46:49]
	v_mfma_f32_16x16x32_bf16 v[42:45], v[188:191], v[196:199], v[42:45]
	v_mfma_f32_16x16x32_bf16 v[30:33], v[180:183], v[210:213], v[30:33]
	v_mfma_f32_16x16x32_bf16 v[26:29], v[188:191], v[210:213], v[26:29]
	v_mfma_f32_16x16x32_bf16 v[14:17], v[180:183], v[218:221], v[14:17]
	v_mfma_f32_16x16x32_bf16 v[10:13], v[188:191], v[218:221], v[10:13]
	v_mfma_f32_16x16x32_bf16 v[6:9], v[180:183], v[226:229], v[6:9]
	v_mfma_f32_16x16x32_bf16 v[2:5], v[188:191], v[226:229], v[2:5]
	s_nop 0
	s_barrier
	v_or_b32_e32 v159, 0x18000, v157
	v_add_u32_e32 v164, 0x18400, v157
	ds_read_b128 v[160:163], v159
	ds_read_b128 v[164:167], v164
	v_add_u32_e32 v159, 0x18800, v157
	v_add_u32_e32 v172, 0x18c00, v157
	ds_read_b128 v[168:171], v159
	ds_read_b128 v[172:175], v172
	v_or_b32_e32 v159, 0x1c000, v157
	v_add_u32_e32 v180, 0x1c400, v157
	ds_read_b128 v[176:179], v159
	ds_read_b128 v[180:183], v180
	v_add_u32_e32 v159, 0x1c800, v157
	v_add_u32_e32 v188, 0x1cc00, v157
	ds_read_b128 v[184:187], v159
	ds_read_b128 v[188:191], v188
	s_add_u32 s18, s24, 0x80000
	s_addc_u32 s19, s25, 0
	s_mov_b32 m0, s34
	v_lshl_add_u64 v[236:237], s[18:19], 0, v[134:135]
	ds_read_b128 v[192:195], v156 offset:32768
	ds_read_b128 v[196:199], v156 offset:33792
	ds_read_b128 v[200:203], v156 offset:34816
	ds_read_b128 v[210:213], v156 offset:35840
	ds_read_b128 v[214:217], v156 offset:36864
	ds_read_b128 v[218:221], v156 offset:37888
	ds_read_b128 v[222:225], v156 offset:38912
	ds_read_b128 v[226:229], v156 offset:39936
	global_load_lds_dwordx4 v[236:237], off
	v_lshl_add_u64 v[236:237], s[18:19], 0, v[132:133]
	s_mov_b32 m0, s35
	s_nop 0
	global_load_lds_dwordx4 v[236:237], off
	s_waitcnt vmcnt(8)
	s_waitcnt lgkmcnt(0)
	s_barrier
	s_nop 0
	s_waitcnt lgkmcnt(0)
	v_mfma_f32_16x16x32_bf16 v[126:129], v[160:163], v[192:195], v[126:129]
	v_mfma_f32_16x16x32_bf16 v[122:125], v[168:171], v[192:195], v[122:125]
	v_mfma_f32_16x16x32_bf16 v[118:121], v[160:163], v[200:203], v[118:121]
	v_mfma_f32_16x16x32_bf16 v[114:117], v[168:171], v[200:203], v[114:117]
	v_mfma_f32_16x16x32_bf16 v[102:105], v[160:163], v[214:217], v[102:105]
	v_mfma_f32_16x16x32_bf16 v[98:101], v[168:171], v[214:217], v[98:101]
	v_mfma_f32_16x16x32_bf16 v[86:89], v[160:163], v[222:225], v[86:89]
	v_mfma_f32_16x16x32_bf16 v[82:85], v[168:171], v[222:225], v[82:85]
	v_mfma_f32_16x16x32_bf16 v[126:129], v[164:167], v[196:199], v[126:129]
	v_mfma_f32_16x16x32_bf16 v[122:125], v[172:175], v[196:199], v[122:125]
	v_mfma_f32_16x16x32_bf16 v[118:121], v[164:167], v[210:213], v[118:121]
	v_mfma_f32_16x16x32_bf16 v[114:117], v[172:175], v[210:213], v[114:117]
	v_mfma_f32_16x16x32_bf16 v[102:105], v[164:167], v[218:221], v[102:105]
	v_mfma_f32_16x16x32_bf16 v[98:101], v[172:175], v[218:221], v[98:101]
	v_mfma_f32_16x16x32_bf16 v[86:89], v[164:167], v[226:229], v[86:89]
	v_mfma_f32_16x16x32_bf16 v[82:85], v[172:175], v[226:229], v[82:85]
	s_nop 0
	s_nop 0
	v_mfma_f32_16x16x32_bf16 v[110:113], v[176:179], v[192:195], v[110:113]
	v_mfma_f32_16x16x32_bf16 v[106:109], v[184:187], v[192:195], v[106:109]
	v_mfma_f32_16x16x32_bf16 v[94:97], v[176:179], v[200:203], v[94:97]
	v_mfma_f32_16x16x32_bf16 v[90:93], v[184:187], v[200:203], v[90:93]
	v_mfma_f32_16x16x32_bf16 v[78:81], v[176:179], v[214:217], v[78:81]
	v_mfma_f32_16x16x32_bf16 v[74:77], v[184:187], v[214:217], v[74:77]
	v_mfma_f32_16x16x32_bf16 v[70:73], v[176:179], v[222:225], v[70:73]
	v_mfma_f32_16x16x32_bf16 v[66:69], v[184:187], v[222:225], v[66:69]
	v_mfma_f32_16x16x32_bf16 v[110:113], v[180:183], v[196:199], v[110:113]
	v_mfma_f32_16x16x32_bf16 v[106:109], v[188:191], v[196:199], v[106:109]
	v_mfma_f32_16x16x32_bf16 v[94:97], v[180:183], v[210:213], v[94:97]
	v_mfma_f32_16x16x32_bf16 v[90:93], v[188:191], v[210:213], v[90:93]
	v_mfma_f32_16x16x32_bf16 v[78:81], v[180:183], v[218:221], v[78:81]
	v_mfma_f32_16x16x32_bf16 v[74:77], v[188:191], v[218:221], v[74:77]
	v_mfma_f32_16x16x32_bf16 v[70:73], v[180:183], v[226:229], v[70:73]
	v_mfma_f32_16x16x32_bf16 v[66:69], v[188:191], v[226:229], v[66:69]
	s_nop 0
	s_barrier
; #define PG8_STAGE(bufoff, gbase, voff) do { _Pragma("unroll") for (int _i = 0; _i < 2; ++_i) \
;         __builtin_amdgcn_global_load_lds((const unsigned*)((const char*)(gbase) + (voff)[_i]), (PG8_LAS unsigned*)(lds + (bufoff) + ldsw + _i * 8192), 16, 0, 0); } while (0)
; #define PG8_LDA(dst, b, h) do { _Pragma("unroll") for (int m = 0; m < 4; ++m) _Pragma("unroll") for (int k = 0; k < 2; ++k) dst[m][k] = *(const PG8_LAS bf16x8*)(lds + PG8_SA(b, h) + aoff + m * 2048 + k * 1024); } while (0)
; #define PG8_LDB(dst, b, h) do { _Pragma("unroll") for (int n = 0; n < 2; ++n) _Pragma("unroll") for (int k = 0; k < 2; ++k) dst[n][k] = *(const PG8_LAS bf16x8*)(lds + PG8_SB(b, h) + boff + n * 2048 + k * 1024); } while (0)
; #define PG8_MMA(ai, bj, At, Bt) do { __builtin_amdgcn_s_setprio(1); _Pragma("unroll") for (int m = 0; m < 4; ++m) _Pragma("unroll") for (int n = 0; n < 2; ++n) _Pragma("unroll") for (int k = 0; k < 2; ++k) \
;         acc[ai][bj][m][n] = __builtin_amdgcn_mfma_f32_16x16x32_bf16(Bt[n][k], At[m][k], acc[ai][bj][m][n], 0, 0, 0); __builtin_amdgcn_s_setprio(0); } while (0)
; #define PG8_WAIT_V(n) asm volatile("s_waitcnt vmcnt(" #n ")" ::: "memory")
; template <class Epi, class Sched, bool ALIGN_EPI = false, bool SP2 = false>
; __device__ __forceinline__ void gemm_phase(PG8_LAS unsigned char* lds, const Gemm g, const Sched& S, const Epi& E) {
;     ...
;             PG8_LDB(B0, 0, 0); PG8_LDB(B1, 0, 1); PG8_SCHED; PG8_LDA(At, 0, 0); PG8_STAGE(PG8_SA(1, 1), a1 + hstep, voffA);
;             PG8_WAIT_V(8); PG8_WAIT_L(0); PG8_BAR; PG8_MMA(0, 0, At, B0); PG8_MMA(0, 1, At, B1); PG8_BAR; PG8_SCHED;
;             PG8_LDA(At, 0, 1); PG8_STAGE(PG8_SB(0, 0), b2, voffB); PG8_STAGE(PG8_SB(0, 1), b2 + hstep, voffB); PG8_STAGE(PG8_SA(0, 0), a2, voffA);
;             PG8_WAIT_V(8); PG8_WAIT_L(0); PG8_BAR; PG8_MMA(1, 0, At, B0); PG8_MMA(1, 1, At, B1); PG8_BAR; PG8_SCHED;
;             PG8_LDB(B0, 1, 0); PG8_LDB(B1, 1, 1); PG8_SCHED; PG8_LDA(At, 1, 0); PG8_STAGE(PG8_SA(0, 1), a2 + hstep, voffA);
;             PG8_WAIT_V(8); PG8_WAIT_L(0); PG8_BAR; PG8_MMA(0, 0, At, B0); PG8_MMA(0, 1, At, B1); PG8_BAR; PG8_SCHED;
;             PG8_LDA(At, 1, 1); PG8_STAGE(PG8_SB(1, 0), b3, voffB); PG8_STAGE(PG8_SB(1, 1), b3 + hstep, voffB); PG8_STAGE(PG8_SA(1, 0), a3, voffA);
;             PG8_WAIT_V(8); PG8_WAIT_L(0); PG8_BAR; PG8_MMA(1, 0, At, B0); PG8_MMA(1, 1, At, B1); PG8_BAR; PG8_SCHED;
	s_mov_b32 m0, s38
	v_lshl_add_u64 v[204:205], v[204:205], 0, s[6:7]
	s_add_u32 s18, s22, 0x80080
	ds_read_b128 v[192:195], v156 offset:49152
	ds_read_b128 v[196:199], v156 offset:50176
	ds_read_b128 v[200:203], v156 offset:51200
	ds_read_b128 v[210:213], v156 offset:52224
	ds_read_b128 v[214:217], v156 offset:53248
	ds_read_b128 v[218:221], v156 offset:54272
	ds_read_b128 v[222:225], v156 offset:55296
	ds_read_b128 v[226:229], v156 offset:56320
	global_load_lds_dwordx4 v[204:205], off
	v_lshl_add_u64 v[204:205], v[230:231], 0, s[6:7]
	s_mov_b32 m0, s39
	s_addc_u32 s19, s23, 0
	global_load_lds_dwordx4 v[204:205], off
	v_lshl_add_u64 v[204:205], s[18:19], 0, v[0:1]
	s_mov_b32 m0, s62
	s_nop 0
	global_load_lds_dwordx4 v[204:205], off
	v_lshl_add_u64 v[204:205], s[18:19], 0, v[130:131]
	s_mov_b32 m0, s78
	s_nop 0
	global_load_lds_dwordx4 v[204:205], off
	v_lshl_add_u64 v[204:205], v[232:233], 0, s[6:7]
	s_mov_b32 m0, s56
	s_nop 0
	global_load_lds_dwordx4 v[204:205], off
	v_lshl_add_u64 v[204:205], v[234:235], 0, s[6:7]
	s_mov_b32 m0, s57
	s_nop 0
	global_load_lds_dwordx4 v[204:205], off
	s_waitcnt vmcnt(8)
	s_waitcnt lgkmcnt(0)
	s_barrier
	s_nop 0
	s_waitcnt lgkmcnt(0)
	v_mfma_f32_16x16x32_bf16 v[62:65], v[160:163], v[192:195], v[62:65]
	v_mfma_f32_16x16x32_bf16 v[58:61], v[168:171], v[192:195], v[58:61]
	v_mfma_f32_16x16x32_bf16 v[54:57], v[160:163], v[200:203], v[54:57]
	v_mfma_f32_16x16x32_bf16 v[50:53], v[168:171], v[200:203], v[50:53]
	v_mfma_f32_16x16x32_bf16 v[38:41], v[160:163], v[214:217], v[38:41]
	v_mfma_f32_16x16x32_bf16 v[34:37], v[168:171], v[214:217], v[34:37]
	v_mfma_f32_16x16x32_bf16 v[22:25], v[160:163], v[222:225], v[22:25]
	v_mfma_f32_16x16x32_bf16 v[18:21], v[168:171], v[222:225], v[18:21]
	v_mfma_f32_16x16x32_bf16 v[62:65], v[164:167], v[196:199], v[62:65]
	v_mfma_f32_16x16x32_bf16 v[58:61], v[172:175], v[196:199], v[58:61]
	v_mfma_f32_16x16x32_bf16 v[54:57], v[164:167], v[210:213], v[54:57]
	v_mfma_f32_16x16x32_bf16 v[50:53], v[172:175], v[210:213], v[50:53]
	v_mfma_f32_16x16x32_bf16 v[38:41], v[164:167], v[218:221], v[38:41]
	v_mfma_f32_16x16x32_bf16 v[34:37], v[172:175], v[218:221], v[34:37]
	v_mfma_f32_16x16x32_bf16 v[22:25], v[164:167], v[226:229], v[22:25]
	v_mfma_f32_16x16x32_bf16 v[18:21], v[172:175], v[226:229], v[18:21]
	s_nop 0
	s_nop 0
	v_mfma_f32_16x16x32_bf16 v[46:49], v[176:179], v[192:195], v[46:49]
	v_mfma_f32_16x16x32_bf16 v[42:45], v[184:187], v[192:195], v[42:45]
	v_mfma_f32_16x16x32_bf16 v[30:33], v[176:179], v[200:203], v[30:33]
	v_mfma_f32_16x16x32_bf16 v[26:29], v[184:187], v[200:203], v[26:29]
	v_mfma_f32_16x16x32_bf16 v[14:17], v[176:179], v[214:217], v[14:17]
	v_mfma_f32_16x16x32_bf16 v[10:13], v[184:187], v[214:217], v[10:13]
	v_mfma_f32_16x16x32_bf16 v[6:9], v[176:179], v[222:225], v[6:9]
	v_mfma_f32_16x16x32_bf16 v[2:5], v[184:187], v[222:225], v[2:5]
	v_mfma_f32_16x16x32_bf16 v[46:49], v[180:183], v[196:199], v[46:49]
	v_mfma_f32_16x16x32_bf16 v[42:45], v[188:191], v[196:199], v[42:45]
	v_mfma_f32_16x16x32_bf16 v[30:33], v[180:183], v[210:213], v[30:33]
	v_mfma_f32_16x16x32_bf16 v[26:29], v[188:191], v[210:213], v[26:29]
	v_mfma_f32_16x16x32_bf16 v[14:17], v[180:183], v[218:221], v[14:17]
	v_mfma_f32_16x16x32_bf16 v[10:13], v[188:191], v[218:221], v[10:13]
	v_mfma_f32_16x16x32_bf16 v[6:9], v[180:183], v[226:229], v[6:9]
	v_mfma_f32_16x16x32_bf16 v[2:5], v[188:191], v[226:229], v[2:5]
	s_nop 0
	s_barrier
	s_add_i32 s96, s96, 2
	s_cmp_gt_u32 s96, 29
	s_mov_b64 s[18:19], s[20:21]
	s_cbranch_scc0 .LBB0_825
	s_and_b64 vcc, exec, s[8:9]
	s_cbranch_vccz .LBB0_828
	s_barrier

; #define PG8_STAGE(bufoff, gbase, voff) do { _Pragma("unroll") for (int _i = 0; _i < 2; ++_i) \
;         __builtin_amdgcn_global_load_lds((const unsigned*)((const char*)(gbase) + (voff)[_i]), (PG8_LAS unsigned*)(lds + (bufoff) + ldsw + _i * 8192), 16, 0, 0); } while (0)
; #define PG8_LDA(dst, b, h) do { _Pragma("unroll") for (int m = 0; m < 4; ++m) _Pragma("unroll") for (int k = 0; k < 2; ++k) dst[m][k] = *(const PG8_LAS bf16x8*)(lds + PG8_SA(b, h) + aoff + m * 2048 + k * 1024); } while (0)
; #define PG8_LDB(dst, b, h) do { _Pragma("unroll") for (int n = 0; n < 2; ++n) _Pragma("unroll") for (int k = 0; k < 2; ++k) dst[n][k] = *(const PG8_LAS bf16x8*)(lds + PG8_SB(b, h) + boff + n * 2048 + k * 1024); } while (0)
; #define PG8_MMA(ai, bj, At, Bt) do { __builtin_amdgcn_s_setprio(1); _Pragma("unroll") for (int m = 0; m < 4; ++m) _Pragma("unroll") for (int n = 0; n < 2; ++n) _Pragma("unroll") for (int k = 0; k < 2; ++k) \
;         acc[ai][bj][m][n] = __builtin_amdgcn_mfma_f32_16x16x32_bf16(Bt[n][k], At[m][k], acc[ai][bj][m][n], 0, 0, 0); __builtin_amdgcn_s_setprio(0); } while (0)
; #define PG8_WAIT_V(n) asm volatile("s_waitcnt vmcnt(" #n ")" ::: "memory")
; template <class Epi, class Sched, bool ALIGN_EPI = false, bool SP2 = false>
; __device__ __forceinline__ void gemm_phase(PG8_LAS unsigned char* lds, const Gemm g, const Sched& S, const Epi& E) {
;     ...
;             PG8_LDB(B0, 0, 0); PG8_LDB(B1, 0, 1); PG8_SCHED; PG8_LDA(At, 0, 0); PG8_STAGE(PG8_SA(1, 1), a1 + hstep, voffA);
;             PG8_WAIT_V(8); PG8_WAIT_L(0); PG8_BAR; PG8_MMA(0, 0, At, B0); PG8_MMA(0, 1, At, B1); PG8_BAR; PG8_SCHED;
;             PG8_LDA(At, 0, 1); PG8_STAGE(PG8_SB(0, 0), b2, voffB); PG8_STAGE(PG8_SB(0, 1), b2 + hstep, voffB); PG8_STAGE(PG8_SA(0, 0), a2, voffA);
;             PG8_WAIT_V(8); PG8_WAIT_L(0); PG8_BAR; PG8_MMA(1, 0, At, B0); PG8_MMA(1, 1, At, B1); PG8_BAR; PG8_SCHED;
;             PG8_LDB(B0, 1, 0); PG8_LDB(B1, 1, 1); PG8_SCHED; PG8_LDA(At, 1, 0); PG8_STAGE(PG8_SA(0, 1), a2 + hstep, voffA);
;             PG8_WAIT_V(8); PG8_WAIT_L(0); PG8_BAR; PG8_MMA(0, 0, At, B0); PG8_MMA(0, 1, At, B1); PG8_BAR; PG8_SCHED;
;             PG8_LDA(At, 1, 1); PG8_STAGE(PG8_SB(1, 0), b3, voffB); PG8_STAGE(PG8_SB(1, 1), b3 + hstep, voffB); PG8_STAGE(PG8_SA(1, 0), a3, voffA);
;             PG8_WAIT_V(8); PG8_WAIT_L(0); PG8_BAR; PG8_MMA(1, 0, At, B0); PG8_MMA(1, 1, At, B1); PG8_BAR; PG8_SCHED;
.LBB0_1092:
	v_or_b32_e32 v159, 0x10000, v157
	v_add_u32_e32 v164, 0x10400, v157
	ds_read_b128 v[160:163], v159
	ds_read_b128 v[164:167], v164
	v_add_u32_e32 v159, 0x10800, v157
	v_add_u32_e32 v172, 0x10c00, v157
	s_add_u32 s12, s10, 0x100
	ds_read_b128 v[168:171], v159
	ds_read_b128 v[172:175], v172
	v_or_b32_e32 v159, 0x14000, v157
	v_add_u32_e32 v180, 0x14400, v157
	s_addc_u32 s13, s11, 0
	ds_read_b128 v[176:179], v159
	ds_read_b128 v[180:183], v180
	v_add_u32_e32 v159, 0x14800, v157
	v_add_u32_e32 v188, 0x14c00, v157
	s_add_u32 s14, s39, s10
	ds_read_b128 v[184:187], v159
	ds_read_b128 v[188:191], v188
	s_addc_u32 s15, s56, s11
	s_cmpk_eq_i32 s57, 0x54
	s_cselect_b32 s16, 0, s12
	s_cselect_b32 s17, 0, s13
	s_cselect_b32 s14, s4, s14
	s_cselect_b32 s15, s5, s15
	s_add_u32 s16, s44, s16
	s_addc_u32 s17, s45, s17
	v_lshl_add_u64 v[204:205], v[152:153], 0, s[10:11]
	s_add_i32 m0, s18, 0xc000
	ds_read_b128 v[192:195], v156
	ds_read_b128 v[196:199], v156 offset:1024
	ds_read_b128 v[200:203], v156 offset:2048
	ds_read_b128 v[210:213], v156 offset:3072
	ds_read_b128 v[214:217], v156 offset:4096
	ds_read_b128 v[218:221], v156 offset:5120
	ds_read_b128 v[222:225], v156 offset:6144
	ds_read_b128 v[226:229], v156 offset:7168
	global_load_lds_dwordx4 v[204:205], off
	v_lshl_add_u64 v[204:205], v[154:155], 0, s[10:11]
	s_add_i32 m0, s18, 0xe000
	s_nop 0
	global_load_lds_dwordx4 v[204:205], off
	s_waitcnt vmcnt(8)
	s_waitcnt lgkmcnt(0)
	s_barrier
	s_nop 0
	s_waitcnt lgkmcnt(0)
	v_mfma_f32_16x16x32_bf16 v[126:129], v[160:163], v[192:195], v[126:129]
	v_mfma_f32_16x16x32_bf16 v[122:125], v[168:171], v[192:195], v[122:125]
	v_mfma_f32_16x16x32_bf16 v[118:121], v[160:163], v[200:203], v[118:121]
	v_mfma_f32_16x16x32_bf16 v[114:117], v[168:171], v[200:203], v[114:117]
	v_mfma_f32_16x16x32_bf16 v[102:105], v[160:163], v[214:217], v[102:105]
	v_mfma_f32_16x16x32_bf16 v[98:101], v[168:171], v[214:217], v[98:101]
	v_mfma_f32_16x16x32_bf16 v[86:89], v[160:163], v[222:225], v[86:89]
	v_mfma_f32_16x16x32_bf16 v[82:85], v[168:171], v[222:225], v[82:85]
	v_mfma_f32_16x16x32_bf16 v[126:129], v[164:167], v[196:199], v[126:129]
	v_mfma_f32_16x16x32_bf16 v[122:125], v[172:175], v[196:199], v[122:125]
	v_mfma_f32_16x16x32_bf16 v[118:121], v[164:167], v[210:213], v[118:121]
	v_mfma_f32_16x16x32_bf16 v[114:117], v[172:175], v[210:213], v[114:117]
	v_mfma_f32_16x16x32_bf16 v[102:105], v[164:167], v[218:221], v[102:105]
	v_mfma_f32_16x16x32_bf16 v[98:101], v[172:175], v[218:221], v[98:101]
	v_mfma_f32_16x16x32_bf16 v[86:89], v[164:167], v[226:229], v[86:89]
	v_mfma_f32_16x16x32_bf16 v[82:85], v[172:175], v[226:229], v[82:85]
	s_nop 0
	s_nop 0
	v_mfma_f32_16x16x32_bf16 v[110:113], v[176:179], v[192:195], v[110:113]
	v_mfma_f32_16x16x32_bf16 v[106:109], v[184:187], v[192:195], v[106:109]
	v_mfma_f32_16x16x32_bf16 v[94:97], v[176:179], v[200:203], v[94:97]
	v_mfma_f32_16x16x32_bf16 v[90:93], v[184:187], v[200:203], v[90:93]
	v_mfma_f32_16x16x32_bf16 v[78:81], v[176:179], v[214:217], v[78:81]
	v_mfma_f32_16x16x32_bf16 v[74:77], v[184:187], v[214:217], v[74:77]
	v_mfma_f32_16x16x32_bf16 v[70:73], v[176:179], v[222:225], v[70:73]
	v_mfma_f32_16x16x32_bf16 v[66:69], v[184:187], v[222:225], v[66:69]
	v_mfma_f32_16x16x32_bf16 v[110:113], v[180:183], v[196:199], v[110:113]
	v_mfma_f32_16x16x32_bf16 v[106:109], v[188:191], v[196:199], v[106:109]
	v_mfma_f32_16x16x32_bf16 v[94:97], v[180:183], v[210:213], v[94:97]
	v_mfma_f32_16x16x32_bf16 v[90:93], v[188:191], v[210:213], v[90:93]
	v_mfma_f32_16x16x32_bf16 v[78:81], v[180:183], v[218:221], v[78:81]
	v_mfma_f32_16x16x32_bf16 v[74:77], v[188:191], v[218:221], v[74:77]
	v_mfma_f32_16x16x32_bf16 v[70:73], v[180:183], v[226:229], v[70:73]
	v_mfma_f32_16x16x32_bf16 v[66:69], v[188:191], v[226:229], v[66:69]
	s_nop 0
	s_barrier
	s_mov_b32 m0, s19
	v_lshl_add_u64 v[204:205], s[14:15], 0, v[0:1]
	s_add_u32 s10, s14, 0x160000
	ds_read_b128 v[192:195], v156 offset:16384
	ds_read_b128 v[196:199], v156 offset:17408
	ds_read_b128 v[200:203], v156 offset:18432
	ds_read_b128 v[210:213], v156 offset:19456
	ds_read_b128 v[214:217], v156 offset:20480
	ds_read_b128 v[218:221], v156 offset:21504
	ds_read_b128 v[222:225], v156 offset:22528
	ds_read_b128 v[226:229], v156 offset:23552
	global_load_lds_dwordx4 v[204:205], off
	v_lshl_add_u64 v[230:231], s[14:15], 0, v[130:131]
	s_mov_b32 m0, s20
	s_addc_u32 s11, s15, 0
	global_load_lds_dwordx4 v[230:231], off
	v_lshl_add_u64 v[232:233], s[10:11], 0, v[0:1]
	s_mov_b32 m0, s21
	v_lshl_add_u64 v[234:235], s[16:17], 0, v[132:133]
	global_load_lds_dwordx4 v[232:233], off
	v_lshl_add_u64 v[232:233], s[10:11], 0, v[130:131]
	s_mov_b32 m0, s22
	s_nop 0
	global_load_lds_dwordx4 v[232:233], off
	v_lshl_add_u64 v[232:233], s[16:17], 0, v[134:135]
	s_mov_b32 m0, s18
	s_nop 0
	global_load_lds_dwordx4 v[232:233], off
	s_mov_b32 m0, s23
	s_nop 0
	global_load_lds_dwordx4 v[234:235], off
	s_waitcnt vmcnt(8)
	s_waitcnt lgkmcnt(0)
	s_barrier
; #define PG8_STAGE(bufoff, gbase, voff) do { _Pragma("unroll") for (int _i = 0; _i < 2; ++_i) \
;         __builtin_amdgcn_global_load_lds((const unsigned*)((const char*)(gbase) + (voff)[_i]), (PG8_LAS unsigned*)(lds + (bufoff) + ldsw + _i * 8192), 16, 0, 0); } while (0)
; #define PG8_LDA(dst, b, h) do { _Pragma("unroll") for (int m = 0; m < 4; ++m) _Pragma("unroll") for (int k = 0; k < 2; ++k) dst[m][k] = *(const PG8_LAS bf16x8*)(lds + PG8_SA(b, h) + aoff + m * 2048 + k * 1024); } while (0)
; #define PG8_LDB(dst, b, h) do { _Pragma("unroll") for (int n = 0; n < 2; ++n) _Pragma("unroll") for (int k = 0; k < 2; ++k) dst[n][k] = *(const PG8_LAS bf16x8*)(lds + PG8_SB(b, h) + boff + n * 2048 + k * 1024); } while (0)
; #define PG8_MMA(ai, bj, At, Bt) do { __builtin_amdgcn_s_setprio(1); _Pragma("unroll") for (int m = 0; m < 4; ++m) _Pragma("unroll") for (int n = 0; n < 2; ++n) _Pragma("unroll") for (int k = 0; k < 2; ++k) \
;         acc[ai][bj][m][n] = __builtin_amdgcn_mfma_f32_16x16x32_bf16(Bt[n][k], At[m][k], acc[ai][bj][m][n], 0, 0, 0); __builtin_amdgcn_s_setprio(0); } while (0)
; #define PG8_WAIT_V(n) asm volatile("s_waitcnt vmcnt(" #n ")" ::: "memory")
; template <class Epi, class Sched, bool ALIGN_EPI = false, bool SP2 = false>
; __device__ __forceinline__ void gemm_phase(PG8_LAS unsigned char* lds, const Gemm g, const Sched& S, const Epi& E) {
;     ...
;             PG8_LDB(B0, 0, 0); PG8_LDB(B1, 0, 1); PG8_SCHED; PG8_LDA(At, 0, 0); PG8_STAGE(PG8_SA(1, 1), a1 + hstep, voffA);
;             PG8_WAIT_V(8); PG8_WAIT_L(0); PG8_BAR; PG8_MMA(0, 0, At, B0); PG8_MMA(0, 1, At, B1); PG8_BAR; PG8_SCHED;
;             PG8_LDA(At, 0, 1); PG8_STAGE(PG8_SB(0, 0), b2, voffB); PG8_STAGE(PG8_SB(0, 1), b2 + hstep, voffB); PG8_STAGE(PG8_SA(0, 0), a2, voffA);
;             PG8_WAIT_V(8); PG8_WAIT_L(0); PG8_BAR; PG8_MMA(1, 0, At, B0); PG8_MMA(1, 1, At, B1); PG8_BAR; PG8_SCHED;
;             PG8_LDB(B0, 1, 0); PG8_LDB(B1, 1, 1); PG8_SCHED; PG8_LDA(At, 1, 0); PG8_STAGE(PG8_SA(0, 1), a2 + hstep, voffA);
;             PG8_WAIT_V(8); PG8_WAIT_L(0); PG8_BAR; PG8_MMA(0, 0, At, B0); PG8_MMA(0, 1, At, B1); PG8_BAR; PG8_SCHED;
;             PG8_LDA(At, 1, 1); PG8_STAGE(PG8_SB(1, 0), b3, voffB); PG8_STAGE(PG8_SB(1, 1), b3 + hstep, voffB); PG8_STAGE(PG8_SA(1, 0), a3, voffA);
;             PG8_WAIT_V(8); PG8_WAIT_L(0); PG8_BAR; PG8_MMA(1, 0, At, B0); PG8_MMA(1, 1, At, B1); PG8_BAR; PG8_SCHED;
	s_nop 0
	s_waitcnt lgkmcnt(0)
	v_mfma_f32_16x16x32_bf16 v[62:65], v[160:163], v[192:195], v[62:65]
	v_mfma_f32_16x16x32_bf16 v[58:61], v[168:171], v[192:195], v[58:61]
	v_mfma_f32_16x16x32_bf16 v[54:57], v[160:163], v[200:203], v[54:57]
	v_mfma_f32_16x16x32_bf16 v[50:53], v[168:171], v[200:203], v[50:53]
	v_mfma_f32_16x16x32_bf16 v[38:41], v[160:163], v[214:217], v[38:41]
	v_mfma_f32_16x16x32_bf16 v[34:37], v[168:171], v[214:217], v[34:37]
	v_mfma_f32_16x16x32_bf16 v[22:25], v[160:163], v[222:225], v[22:25]
	v_mfma_f32_16x16x32_bf16 v[18:21], v[168:171], v[222:225], v[18:21]
	v_mfma_f32_16x16x32_bf16 v[62:65], v[164:167], v[196:199], v[62:65]
	v_mfma_f32_16x16x32_bf16 v[58:61], v[172:175], v[196:199], v[58:61]
	v_mfma_f32_16x16x32_bf16 v[54:57], v[164:167], v[210:213], v[54:57]
	v_mfma_f32_16x16x32_bf16 v[50:53], v[172:175], v[210:213], v[50:53]
	v_mfma_f32_16x16x32_bf16 v[38:41], v[164:167], v[218:221], v[38:41]
	v_mfma_f32_16x16x32_bf16 v[34:37], v[172:175], v[218:221], v[34:37]
	v_mfma_f32_16x16x32_bf16 v[22:25], v[164:167], v[226:229], v[22:25]
	v_mfma_f32_16x16x32_bf16 v[18:21], v[172:175], v[226:229], v[18:21]
	s_nop 0
	s_nop 0
	v_mfma_f32_16x16x32_bf16 v[46:49], v[176:179], v[192:195], v[46:49]
	v_mfma_f32_16x16x32_bf16 v[42:45], v[184:187], v[192:195], v[42:45]
	v_mfma_f32_16x16x32_bf16 v[30:33], v[176:179], v[200:203], v[30:33]
	v_mfma_f32_16x16x32_bf16 v[26:29], v[184:187], v[200:203], v[26:29]
	v_mfma_f32_16x16x32_bf16 v[14:17], v[176:179], v[214:217], v[14:17]
	v_mfma_f32_16x16x32_bf16 v[10:13], v[184:187], v[214:217], v[10:13]
	v_mfma_f32_16x16x32_bf16 v[6:9], v[176:179], v[222:225], v[6:9]
	v_mfma_f32_16x16x32_bf16 v[2:5], v[184:187], v[222:225], v[2:5]
	v_mfma_f32_16x16x32_bf16 v[46:49], v[180:183], v[196:199], v[46:49]
	v_mfma_f32_16x16x32_bf16 v[42:45], v[188:191], v[196:199], v[42:45]
	v_mfma_f32_16x16x32_bf16 v[30:33], v[180:183], v[210:213], v[30:33]
	v_mfma_f32_16x16x32_bf16 v[26:29], v[188:191], v[210:213], v[26:29]
	v_mfma_f32_16x16x32_bf16 v[14:17], v[180:183], v[218:221], v[14:17]
	v_mfma_f32_16x16x32_bf16 v[10:13], v[188:191], v[218:221], v[10:13]
	v_mfma_f32_16x16x32_bf16 v[6:9], v[180:183], v[226:229], v[6:9]
	v_mfma_f32_16x16x32_bf16 v[2:5], v[188:191], v[226:229], v[2:5]
	s_nop 0
	s_barrier
	v_or_b32_e32 v159, 0x18000, v157
	v_add_u32_e32 v164, 0x18400, v157
	ds_read_b128 v[160:163], v159
	ds_read_b128 v[164:167], v164
	v_add_u32_e32 v159, 0x18800, v157
	v_add_u32_e32 v172, 0x18c00, v157
	ds_read_b128 v[168:171], v159
	ds_read_b128 v[172:175], v172
	v_or_b32_e32 v159, 0x1c000, v157
	v_add_u32_e32 v180, 0x1c400, v157
	ds_read_b128 v[176:179], v159
	ds_read_b128 v[180:183], v180
	v_add_u32_e32 v159, 0x1c800, v157
	v_add_u32_e32 v188, 0x1cc00, v157
	ds_read_b128 v[184:187], v159
	ds_read_b128 v[188:191], v188
	s_add_u32 s10, s16, 0x160000
	s_addc_u32 s11, s17, 0
	s_mov_b32 m0, s24
	v_lshl_add_u64 v[236:237], s[10:11], 0, v[134:135]
	ds_read_b128 v[192:195], v156 offset:32768
	ds_read_b128 v[196:199], v156 offset:33792
	ds_read_b128 v[200:203], v156 offset:34816
	ds_read_b128 v[210:213], v156 offset:35840
	ds_read_b128 v[214:217], v156 offset:36864
	ds_read_b128 v[218:221], v156 offset:37888
	ds_read_b128 v[222:225], v156 offset:38912
	ds_read_b128 v[226:229], v156 offset:39936
	global_load_lds_dwordx4 v[236:237], off
	v_lshl_add_u64 v[236:237], s[10:11], 0, v[132:133]
	s_mov_b32 m0, s25
	s_nop 0
	global_load_lds_dwordx4 v[236:237], off
	s_waitcnt vmcnt(8)
	s_waitcnt lgkmcnt(0)
	s_barrier
	s_nop 0
	s_waitcnt lgkmcnt(0)
	v_mfma_f32_16x16x32_bf16 v[126:129], v[160:163], v[192:195], v[126:129]
	v_mfma_f32_16x16x32_bf16 v[122:125], v[168:171], v[192:195], v[122:125]
	v_mfma_f32_16x16x32_bf16 v[118:121], v[160:163], v[200:203], v[118:121]
	v_mfma_f32_16x16x32_bf16 v[114:117], v[168:171], v[200:203], v[114:117]
	v_mfma_f32_16x16x32_bf16 v[102:105], v[160:163], v[214:217], v[102:105]
	v_mfma_f32_16x16x32_bf16 v[98:101], v[168:171], v[214:217], v[98:101]
	v_mfma_f32_16x16x32_bf16 v[86:89], v[160:163], v[222:225], v[86:89]
	v_mfma_f32_16x16x32_bf16 v[82:85], v[168:171], v[222:225], v[82:85]
	v_mfma_f32_16x16x32_bf16 v[126:129], v[164:167], v[196:199], v[126:129]
	v_mfma_f32_16x16x32_bf16 v[122:125], v[172:175], v[196:199], v[122:125]
	v_mfma_f32_16x16x32_bf16 v[118:121], v[164:167], v[210:213], v[118:121]
	v_mfma_f32_16x16x32_bf16 v[114:117], v[172:175], v[210:213], v[114:117]
	v_mfma_f32_16x16x32_bf16 v[102:105], v[164:167], v[218:221], v[102:105]
	v_mfma_f32_16x16x32_bf16 v[98:101], v[172:175], v[218:221], v[98:101]
	v_mfma_f32_16x16x32_bf16 v[86:89], v[164:167], v[226:229], v[86:89]
	v_mfma_f32_16x16x32_bf16 v[82:85], v[172:175], v[226:229], v[82:85]
	s_nop 0
	s_nop 0
	v_mfma_f32_16x16x32_bf16 v[110:113], v[176:179], v[192:195], v[110:113]
	v_mfma_f32_16x16x32_bf16 v[106:109], v[184:187], v[192:195], v[106:109]
	v_mfma_f32_16x16x32_bf16 v[94:97], v[176:179], v[200:203], v[94:97]
	v_mfma_f32_16x16x32_bf16 v[90:93], v[184:187], v[200:203], v[90:93]
	v_mfma_f32_16x16x32_bf16 v[78:81], v[176:179], v[214:217], v[78:81]
	v_mfma_f32_16x16x32_bf16 v[74:77], v[184:187], v[214:217], v[74:77]
	v_mfma_f32_16x16x32_bf16 v[70:73], v[176:179], v[222:225], v[70:73]
	v_mfma_f32_16x16x32_bf16 v[66:69], v[184:187], v[222:225], v[66:69]
	v_mfma_f32_16x16x32_bf16 v[110:113], v[180:183], v[196:199], v[110:113]
	v_mfma_f32_16x16x32_bf16 v[106:109], v[188:191], v[196:199], v[106:109]
	v_mfma_f32_16x16x32_bf16 v[94:97], v[180:183], v[210:213], v[94:97]
	v_mfma_f32_16x16x32_bf16 v[90:93], v[188:191], v[210:213], v[90:93]
	v_mfma_f32_16x16x32_bf16 v[78:81], v[180:183], v[218:221], v[78:81]
	v_mfma_f32_16x16x32_bf16 v[74:77], v[188:191], v[218:221], v[74:77]
	v_mfma_f32_16x16x32_bf16 v[70:73], v[180:183], v[226:229], v[70:73]
	v_mfma_f32_16x16x32_bf16 v[66:69], v[188:191], v[226:229], v[66:69]
	s_nop 0
	s_barrier
; #define PG8_STAGE(bufoff, gbase, voff) do { _Pragma("unroll") for (int _i = 0; _i < 2; ++_i) \
;         __builtin_amdgcn_global_load_lds((const unsigned*)((const char*)(gbase) + (voff)[_i]), (PG8_LAS unsigned*)(lds + (bufoff) + ldsw + _i * 8192), 16, 0, 0); } while (0)
; #define PG8_LDA(dst, b, h) do { _Pragma("unroll") for (int m = 0; m < 4; ++m) _Pragma("unroll") for (int k = 0; k < 2; ++k) dst[m][k] = *(const PG8_LAS bf16x8*)(lds + PG8_SA(b, h) + aoff + m * 2048 + k * 1024); } while (0)
; #define PG8_LDB(dst, b, h) do { _Pragma("unroll") for (int n = 0; n < 2; ++n) _Pragma("unroll") for (int k = 0; k < 2; ++k) dst[n][k] = *(const PG8_LAS bf16x8*)(lds + PG8_SB(b, h) + boff + n * 2048 + k * 1024); } while (0)
; #define PG8_MMA(ai, bj, At, Bt) do { __builtin_amdgcn_s_setprio(1); _Pragma("unroll") for (int m = 0; m < 4; ++m) _Pragma("unroll") for (int n = 0; n < 2; ++n) _Pragma("unroll") for (int k = 0; k < 2; ++k) \
;         acc[ai][bj][m][n] = __builtin_amdgcn_mfma_f32_16x16x32_bf16(Bt[n][k], At[m][k], acc[ai][bj][m][n], 0, 0, 0); __builtin_amdgcn_s_setprio(0); } while (0)
; #define PG8_WAIT_V(n) asm volatile("s_waitcnt vmcnt(" #n ")" ::: "memory")
; template <class Epi, class Sched, bool ALIGN_EPI = false, bool SP2 = false>
; __device__ __forceinline__ void gemm_phase(PG8_LAS unsigned char* lds, const Gemm g, const Sched& S, const Epi& E) {
;     ...
;             PG8_LDB(B0, 0, 0); PG8_LDB(B1, 0, 1); PG8_SCHED; PG8_LDA(At, 0, 0); PG8_STAGE(PG8_SA(1, 1), a1 + hstep, voffA);
;             PG8_WAIT_V(8); PG8_WAIT_L(0); PG8_BAR; PG8_MMA(0, 0, At, B0); PG8_MMA(0, 1, At, B1); PG8_BAR; PG8_SCHED;
;             PG8_LDA(At, 0, 1); PG8_STAGE(PG8_SB(0, 0), b2, voffB); PG8_STAGE(PG8_SB(0, 1), b2 + hstep, voffB); PG8_STAGE(PG8_SA(0, 0), a2, voffA);
;             PG8_WAIT_V(8); PG8_WAIT_L(0); PG8_BAR; PG8_MMA(1, 0, At, B0); PG8_MMA(1, 1, At, B1); PG8_BAR; PG8_SCHED;
;             PG8_LDB(B0, 1, 0); PG8_LDB(B1, 1, 1); PG8_SCHED; PG8_LDA(At, 1, 0); PG8_STAGE(PG8_SA(0, 1), a2 + hstep, voffA);
;             PG8_WAIT_V(8); PG8_WAIT_L(0); PG8_BAR; PG8_MMA(0, 0, At, B0); PG8_MMA(0, 1, At, B1); PG8_BAR; PG8_SCHED;
;             PG8_LDA(At, 1, 1); PG8_STAGE(PG8_SB(1, 0), b3, voffB); PG8_STAGE(PG8_SB(1, 1), b3 + hstep, voffB); PG8_STAGE(PG8_SA(1, 0), a3, voffA);
;             PG8_WAIT_V(8); PG8_WAIT_L(0); PG8_BAR; PG8_MMA(1, 0, At, B0); PG8_MMA(1, 1, At, B1); PG8_BAR; PG8_SCHED;
	s_mov_b32 m0, s26
	v_lshl_add_u64 v[204:205], v[204:205], 0, s[6:7]
	s_add_u32 s10, s14, 0x160080
	ds_read_b128 v[192:195], v156 offset:49152
	ds_read_b128 v[196:199], v156 offset:50176
	ds_read_b128 v[200:203], v156 offset:51200
	ds_read_b128 v[210:213], v156 offset:52224
	ds_read_b128 v[214:217], v156 offset:53248
	ds_read_b128 v[218:221], v156 offset:54272
	ds_read_b128 v[222:225], v156 offset:55296
	ds_read_b128 v[226:229], v156 offset:56320
	global_load_lds_dwordx4 v[204:205], off
	v_lshl_add_u64 v[204:205], v[230:231], 0, s[6:7]
	s_mov_b32 m0, s27
	s_addc_u32 s11, s15, 0
	global_load_lds_dwordx4 v[204:205], off
	v_lshl_add_u64 v[204:205], s[10:11], 0, v[0:1]
	s_mov_b32 m0, s30
	s_nop 0
	global_load_lds_dwordx4 v[204:205], off
	v_lshl_add_u64 v[204:205], s[10:11], 0, v[130:131]
	s_mov_b32 m0, s31
	s_nop 0
	global_load_lds_dwordx4 v[204:205], off
	v_lshl_add_u64 v[204:205], v[232:233], 0, s[6:7]
	s_mov_b32 m0, s28
	s_nop 0
	global_load_lds_dwordx4 v[204:205], off
	v_lshl_add_u64 v[204:205], v[234:235], 0, s[6:7]
	s_mov_b32 m0, s29
	s_nop 0
	global_load_lds_dwordx4 v[204:205], off
	s_waitcnt vmcnt(8)
	s_waitcnt lgkmcnt(0)
	s_barrier
	s_nop 0
	s_waitcnt lgkmcnt(0)
	v_mfma_f32_16x16x32_bf16 v[62:65], v[160:163], v[192:195], v[62:65]
	v_mfma_f32_16x16x32_bf16 v[58:61], v[168:171], v[192:195], v[58:61]
	v_mfma_f32_16x16x32_bf16 v[54:57], v[160:163], v[200:203], v[54:57]
	v_mfma_f32_16x16x32_bf16 v[50:53], v[168:171], v[200:203], v[50:53]
	v_mfma_f32_16x16x32_bf16 v[38:41], v[160:163], v[214:217], v[38:41]
	v_mfma_f32_16x16x32_bf16 v[34:37], v[168:171], v[214:217], v[34:37]
	v_mfma_f32_16x16x32_bf16 v[22:25], v[160:163], v[222:225], v[22:25]
	v_mfma_f32_16x16x32_bf16 v[18:21], v[168:171], v[222:225], v[18:21]
	v_mfma_f32_16x16x32_bf16 v[62:65], v[164:167], v[196:199], v[62:65]
	v_mfma_f32_16x16x32_bf16 v[58:61], v[172:175], v[196:199], v[58:61]
	v_mfma_f32_16x16x32_bf16 v[54:57], v[164:167], v[210:213], v[54:57]
	v_mfma_f32_16x16x32_bf16 v[50:53], v[172:175], v[210:213], v[50:53]
	v_mfma_f32_16x16x32_bf16 v[38:41], v[164:167], v[218:221], v[38:41]
	v_mfma_f32_16x16x32_bf16 v[34:37], v[172:175], v[218:221], v[34:37]
	v_mfma_f32_16x16x32_bf16 v[22:25], v[164:167], v[226:229], v[22:25]
	v_mfma_f32_16x16x32_bf16 v[18:21], v[172:175], v[226:229], v[18:21]
	s_nop 0
	s_nop 0
	v_mfma_f32_16x16x32_bf16 v[46:49], v[176:179], v[192:195], v[46:49]
	v_mfma_f32_16x16x32_bf16 v[42:45], v[184:187], v[192:195], v[42:45]
	v_mfma_f32_16x16x32_bf16 v[30:33], v[176:179], v[200:203], v[30:33]
	v_mfma_f32_16x16x32_bf16 v[26:29], v[184:187], v[200:203], v[26:29]
	v_mfma_f32_16x16x32_bf16 v[14:17], v[176:179], v[214:217], v[14:17]
	v_mfma_f32_16x16x32_bf16 v[10:13], v[184:187], v[214:217], v[10:13]
	v_mfma_f32_16x16x32_bf16 v[6:9], v[176:179], v[222:225], v[6:9]
	v_mfma_f32_16x16x32_bf16 v[2:5], v[184:187], v[222:225], v[2:5]
	v_mfma_f32_16x16x32_bf16 v[46:49], v[180:183], v[196:199], v[46:49]
	v_mfma_f32_16x16x32_bf16 v[42:45], v[188:191], v[196:199], v[42:45]
	v_mfma_f32_16x16x32_bf16 v[30:33], v[180:183], v[210:213], v[30:33]
	v_mfma_f32_16x16x32_bf16 v[26:29], v[188:191], v[210:213], v[26:29]
	v_mfma_f32_16x16x32_bf16 v[14:17], v[180:183], v[218:221], v[14:17]
	v_mfma_f32_16x16x32_bf16 v[10:13], v[188:191], v[218:221], v[10:13]
	v_mfma_f32_16x16x32_bf16 v[6:9], v[180:183], v[226:229], v[6:9]
	v_mfma_f32_16x16x32_bf16 v[2:5], v[188:191], v[226:229], v[2:5]
	s_nop 0
	s_barrier
	s_add_i32 s57, s57, 2
	s_cmpk_gt_u32 s57, 0x55
	s_mov_b64 s[10:11], s[12:13]
	s_cbranch_scc0 .LBB0_1092
	s_and_b64 vcc, exec, s[2:3]
	s_cbranch_vccz .LBB0_1095
	s_barrier
